# GEMM MMA blocks: barrier 8 MFMAs before block end (was 4)
# baseline (speedup 1.0000x reference)
.LBB0_323:
	ds_read_b128 v[96:99], v209
	ds_read_b128 v[100:103], v209 offset:1024
	ds_read_b128 v[120:123], v209 offset:2048
	ds_read_b128 v[124:127], v209 offset:3072
	ds_read_b128 v[144:147], v210
	ds_read_b128 v[148:151], v210 offset:1024
	ds_read_b128 v[152:155], v210 offset:2048
	ds_read_b128 v[156:159], v210 offset:3072
	s_add_u32 s8, s6, 0xfffc0080
	s_addc_u32 s9, s7, -1
	s_cmp_eq_u32 s78, 12
	s_cselect_b32 s51, s18, s9
	s_cselect_b32 s50, s43, s8
	s_cselect_b32 s9, s45, s57
	s_cselect_b32 s8, s55, s56
	v_lshl_add_u64 v[206:207], s[6:7], 0, v[170:171]
	s_add_i32 m0, s17, 0xc000
	ds_read_b128 v[178:181], v211
	ds_read_b128 v[182:185], v211 offset:1024
	ds_read_b128 v[186:189], v211 offset:2048
	ds_read_b128 v[190:193], v211 offset:3072
	ds_read_b128 v[194:197], v211 offset:4096
	ds_read_b128 v[198:201], v211 offset:5120
	ds_read_b128 v[202:205], v211 offset:6144
	ds_read_b128 v[218:221], v211 offset:7168
	global_load_lds_dwordx4 v[206:207], off
	v_lshl_add_u64 v[206:207], s[6:7], 0, v[172:173]
	s_add_i32 m0, s17, 0xe000
	s_nop 0
	global_load_lds_dwordx4 v[206:207], off
	s_waitcnt vmcnt(8)
	s_waitcnt lgkmcnt(0)
	s_barrier
	s_setprio 1
	s_waitcnt lgkmcnt(0)
	v_mfma_f32_16x16x32_bf16 v[140:143], v[96:99], v[178:181], v[140:143]
	v_mfma_f32_16x16x32_bf16 v[136:139], v[120:123], v[178:181], v[136:139]
	v_mfma_f32_16x16x32_bf16 v[116:119], v[96:99], v[186:189], v[116:119]
	v_mfma_f32_16x16x32_bf16 v[112:115], v[120:123], v[186:189], v[112:115]
	v_mfma_f32_16x16x32_bf16 v[92:95], v[96:99], v[194:197], v[92:95]
	v_mfma_f32_16x16x32_bf16 v[88:91], v[120:123], v[194:197], v[88:91]
	v_mfma_f32_16x16x32_bf16 v[76:79], v[96:99], v[202:205], v[76:79]
	v_mfma_f32_16x16x32_bf16 v[72:75], v[120:123], v[202:205], v[72:75]
	v_mfma_f32_16x16x32_bf16 v[140:143], v[100:103], v[182:185], v[140:143]
	v_mfma_f32_16x16x32_bf16 v[136:139], v[124:127], v[182:185], v[136:139]
	v_mfma_f32_16x16x32_bf16 v[116:119], v[100:103], v[190:193], v[116:119]
	v_mfma_f32_16x16x32_bf16 v[112:115], v[124:127], v[190:193], v[112:115]
	v_mfma_f32_16x16x32_bf16 v[92:95], v[100:103], v[198:201], v[92:95]
	v_mfma_f32_16x16x32_bf16 v[88:91], v[124:127], v[198:201], v[88:91]
	v_mfma_f32_16x16x32_bf16 v[76:79], v[100:103], v[218:221], v[76:79]
	v_mfma_f32_16x16x32_bf16 v[72:75], v[124:127], v[218:221], v[72:75]
	s_setprio 0
	s_setprio 1
	v_mfma_f32_16x16x32_bf16 v[132:135], v[144:147], v[178:181], v[132:135]
	v_mfma_f32_16x16x32_bf16 v[128:131], v[152:155], v[178:181], v[128:131]
	v_mfma_f32_16x16x32_bf16 v[108:111], v[144:147], v[186:189], v[108:111]
	v_mfma_f32_16x16x32_bf16 v[104:107], v[152:155], v[186:189], v[104:107]
	v_mfma_f32_16x16x32_bf16 v[84:87], v[144:147], v[194:197], v[84:87]
	v_mfma_f32_16x16x32_bf16 v[80:83], v[152:155], v[194:197], v[80:83]
	v_mfma_f32_16x16x32_bf16 v[68:71], v[144:147], v[202:205], v[68:71]
	v_mfma_f32_16x16x32_bf16 v[64:67], v[152:155], v[202:205], v[64:67]
	s_setprio 2
	s_barrier
	v_mfma_f32_16x16x32_bf16 v[132:135], v[148:151], v[182:185], v[132:135]
	v_mfma_f32_16x16x32_bf16 v[128:131], v[156:159], v[182:185], v[128:131]
	v_mfma_f32_16x16x32_bf16 v[108:111], v[148:151], v[190:193], v[108:111]
	v_mfma_f32_16x16x32_bf16 v[104:107], v[156:159], v[190:193], v[104:107]
	v_mfma_f32_16x16x32_bf16 v[84:87], v[148:151], v[198:201], v[84:87]
	v_mfma_f32_16x16x32_bf16 v[80:83], v[156:159], v[198:201], v[80:83]
	v_mfma_f32_16x16x32_bf16 v[68:71], v[148:151], v[218:221], v[68:71]
	v_mfma_f32_16x16x32_bf16 v[64:67], v[156:159], v[218:221], v[64:67]
	s_setprio 0
	s_add_i32 s79, s73, s61
	v_lshl_add_u64 v[206:207], s[8:9], 0, v[162:163]
	s_mov_b32 m0, s79
	ds_read_b128 v[178:181], v211 offset:16384
	ds_read_b128 v[182:185], v211 offset:17408
	ds_read_b128 v[186:189], v211 offset:18432
	ds_read_b128 v[190:193], v211 offset:19456
	ds_read_b128 v[194:197], v211 offset:20480
	ds_read_b128 v[198:201], v211 offset:21504
	ds_read_b128 v[202:205], v211 offset:22528
	ds_read_b128 v[218:221], v211 offset:23552
	global_load_lds_dwordx4 v[206:207], off
	s_add_i32 m0, s79, 0x2000
	s_add_u32 s80, s8, 0x40000
	v_lshl_add_u64 v[222:223], s[8:9], 0, v[166:167]
	s_addc_u32 s81, s9, 0
	s_add_i32 s79, s74, s61
	global_load_lds_dwordx4 v[222:223], off
	v_lshl_add_u64 v[224:225], s[80:81], 0, v[162:163]
	s_mov_b32 m0, s79
	v_lshl_add_u64 v[226:227], s[50:51], 0, v[164:165]
	global_load_lds_dwordx4 v[224:225], off
	v_lshl_add_u64 v[224:225], s[80:81], 0, v[166:167]
	s_add_i32 m0, s79, 0x2000
	s_nop 0
	global_load_lds_dwordx4 v[224:225], off
	v_lshl_add_u64 v[224:225], s[50:51], 0, v[160:161]
	s_mov_b32 m0, s17
	s_nop 0
	global_load_lds_dwordx4 v[224:225], off
	s_mov_b32 m0, s62
	s_nop 0
	global_load_lds_dwordx4 v[226:227], off
	s_waitcnt vmcnt(8)
	s_waitcnt lgkmcnt(0)
	s_barrier
	s_setprio 1
	s_waitcnt lgkmcnt(0)
	v_mfma_f32_16x16x32_bf16 v[60:63], v[96:99], v[178:181], v[60:63]
	v_mfma_f32_16x16x32_bf16 v[56:59], v[120:123], v[178:181], v[56:59]
	v_mfma_f32_16x16x32_bf16 v[44:47], v[96:99], v[186:189], v[44:47]
	v_mfma_f32_16x16x32_bf16 v[40:43], v[120:123], v[186:189], v[40:43]
	v_mfma_f32_16x16x32_bf16 v[28:31], v[96:99], v[194:197], v[28:31]
	v_mfma_f32_16x16x32_bf16 v[24:27], v[120:123], v[194:197], v[24:27]
	v_mfma_f32_16x16x32_bf16 v[12:15], v[96:99], v[202:205], v[12:15]
	v_mfma_f32_16x16x32_bf16 v[8:11], v[120:123], v[202:205], v[8:11]
	v_mfma_f32_16x16x32_bf16 v[60:63], v[100:103], v[182:185], v[60:63]
	v_mfma_f32_16x16x32_bf16 v[56:59], v[124:127], v[182:185], v[56:59]
	v_mfma_f32_16x16x32_bf16 v[44:47], v[100:103], v[190:193], v[44:47]
	v_mfma_f32_16x16x32_bf16 v[40:43], v[124:127], v[190:193], v[40:43]
	v_mfma_f32_16x16x32_bf16 v[28:31], v[100:103], v[198:201], v[28:31]
	v_mfma_f32_16x16x32_bf16 v[24:27], v[124:127], v[198:201], v[24:27]
	v_mfma_f32_16x16x32_bf16 v[12:15], v[100:103], v[218:221], v[12:15]
	v_mfma_f32_16x16x32_bf16 v[8:11], v[124:127], v[218:221], v[8:11]
	s_setprio 0
	s_setprio 1
	v_mfma_f32_16x16x32_bf16 v[52:55], v[144:147], v[178:181], v[52:55]
	v_mfma_f32_16x16x32_bf16 v[48:51], v[152:155], v[178:181], v[48:51]
	v_mfma_f32_16x16x32_bf16 v[36:39], v[144:147], v[186:189], v[36:39]
	v_mfma_f32_16x16x32_bf16 v[32:35], v[152:155], v[186:189], v[32:35]
	v_mfma_f32_16x16x32_bf16 v[20:23], v[144:147], v[194:197], v[20:23]
	v_mfma_f32_16x16x32_bf16 v[16:19], v[152:155], v[194:197], v[16:19]
	v_mfma_f32_16x16x32_bf16 v[4:7], v[144:147], v[202:205], v[4:7]
	v_mfma_f32_16x16x32_bf16 v[0:3], v[152:155], v[202:205], v[0:3]
	s_setprio 2
	s_barrier
	v_mfma_f32_16x16x32_bf16 v[52:55], v[148:151], v[182:185], v[52:55]
	v_mfma_f32_16x16x32_bf16 v[48:51], v[156:159], v[182:185], v[48:51]
	v_mfma_f32_16x16x32_bf16 v[36:39], v[148:151], v[190:193], v[36:39]
	v_mfma_f32_16x16x32_bf16 v[32:35], v[156:159], v[190:193], v[32:35]
	v_mfma_f32_16x16x32_bf16 v[20:23], v[148:151], v[198:201], v[20:23]
	v_mfma_f32_16x16x32_bf16 v[16:19], v[156:159], v[198:201], v[16:19]
	v_mfma_f32_16x16x32_bf16 v[4:7], v[148:151], v[218:221], v[4:7]
	v_mfma_f32_16x16x32_bf16 v[0:3], v[156:159], v[218:221], v[0:3]
	s_setprio 0
	s_add_i32 s79, 0, 0x18000
	s_add_i32 s80, 0, 0x1c000
	v_add_u32_e32 v124, s79, v208
	v_add_u32_e32 v156, s80, v208
	ds_read_b128 v[96:99], v124
	ds_read_b128 v[100:103], v124 offset:1024
	ds_read_b128 v[120:123], v124 offset:2048
	ds_read_b128 v[124:127], v124 offset:3072
	ds_read_b128 v[144:147], v156
	ds_read_b128 v[148:151], v156 offset:1024
	ds_read_b128 v[152:155], v156 offset:2048
	ds_read_b128 v[156:159], v156 offset:3072
	s_add_u32 s50, s50, 0x40000
	s_addc_u32 s51, s51, 0
	s_mov_b32 m0, s63
	v_lshl_add_u64 v[228:229], s[50:51], 0, v[160:161]
	ds_read_b128 v[178:181], v211 offset:32768
	ds_read_b128 v[182:185], v211 offset:33792
	ds_read_b128 v[186:189], v211 offset:34816
	ds_read_b128 v[190:193], v211 offset:35840
	ds_read_b128 v[194:197], v211 offset:36864
	ds_read_b128 v[198:201], v211 offset:37888
	ds_read_b128 v[202:205], v211 offset:38912
	ds_read_b128 v[218:221], v211 offset:39936
	global_load_lds_dwordx4 v[228:229], off
	v_lshl_add_u64 v[228:229], s[50:51], 0, v[164:165]
	s_mov_b32 m0, s64
	s_nop 0
	global_load_lds_dwordx4 v[228:229], off
	s_waitcnt vmcnt(8)
	s_waitcnt lgkmcnt(0)
	s_barrier
	s_setprio 1
	s_waitcnt lgkmcnt(0)
	v_mfma_f32_16x16x32_bf16 v[140:143], v[96:99], v[178:181], v[140:143]
	v_mfma_f32_16x16x32_bf16 v[136:139], v[120:123], v[178:181], v[136:139]
	v_mfma_f32_16x16x32_bf16 v[116:119], v[96:99], v[186:189], v[116:119]
	v_mfma_f32_16x16x32_bf16 v[112:115], v[120:123], v[186:189], v[112:115]
	v_mfma_f32_16x16x32_bf16 v[92:95], v[96:99], v[194:197], v[92:95]
	v_mfma_f32_16x16x32_bf16 v[88:91], v[120:123], v[194:197], v[88:91]
	v_mfma_f32_16x16x32_bf16 v[76:79], v[96:99], v[202:205], v[76:79]
	v_mfma_f32_16x16x32_bf16 v[72:75], v[120:123], v[202:205], v[72:75]
	v_mfma_f32_16x16x32_bf16 v[140:143], v[100:103], v[182:185], v[140:143]
	v_mfma_f32_16x16x32_bf16 v[136:139], v[124:127], v[182:185], v[136:139]
	v_mfma_f32_16x16x32_bf16 v[116:119], v[100:103], v[190:193], v[116:119]
	v_mfma_f32_16x16x32_bf16 v[112:115], v[124:127], v[190:193], v[112:115]
	v_mfma_f32_16x16x32_bf16 v[92:95], v[100:103], v[198:201], v[92:95]
	v_mfma_f32_16x16x32_bf16 v[88:91], v[124:127], v[198:201], v[88:91]
	v_mfma_f32_16x16x32_bf16 v[76:79], v[100:103], v[218:221], v[76:79]
	v_mfma_f32_16x16x32_bf16 v[72:75], v[124:127], v[218:221], v[72:75]
	s_setprio 0
	s_setprio 1
	v_mfma_f32_16x16x32_bf16 v[132:135], v[144:147], v[178:181], v[132:135]
	v_mfma_f32_16x16x32_bf16 v[128:131], v[152:155], v[178:181], v[128:131]
	v_mfma_f32_16x16x32_bf16 v[108:111], v[144:147], v[186:189], v[108:111]
	v_mfma_f32_16x16x32_bf16 v[104:107], v[152:155], v[186:189], v[104:107]
	v_mfma_f32_16x16x32_bf16 v[84:87], v[144:147], v[194:197], v[84:87]
	v_mfma_f32_16x16x32_bf16 v[80:83], v[152:155], v[194:197], v[80:83]
	v_mfma_f32_16x16x32_bf16 v[68:71], v[144:147], v[202:205], v[68:71]
	v_mfma_f32_16x16x32_bf16 v[64:67], v[152:155], v[202:205], v[64:67]
	s_setprio 2
	s_barrier
	v_mfma_f32_16x16x32_bf16 v[132:135], v[148:151], v[182:185], v[132:135]
	v_mfma_f32_16x16x32_bf16 v[128:131], v[156:159], v[182:185], v[128:131]
	v_mfma_f32_16x16x32_bf16 v[108:111], v[148:151], v[190:193], v[108:111]
	v_mfma_f32_16x16x32_bf16 v[104:107], v[156:159], v[190:193], v[104:107]
	v_mfma_f32_16x16x32_bf16 v[84:87], v[148:151], v[198:201], v[84:87]
	v_mfma_f32_16x16x32_bf16 v[80:83], v[156:159], v[198:201], v[80:83]
	v_mfma_f32_16x16x32_bf16 v[68:71], v[148:151], v[218:221], v[68:71]
	v_mfma_f32_16x16x32_bf16 v[64:67], v[156:159], v[218:221], v[64:67]
	s_setprio 0
	s_add_i32 s50, s79, s61
	v_lshl_add_u64 v[206:207], v[206:207], 0, s[36:37]
	s_mov_b32 m0, s50
	ds_read_b128 v[178:181], v211 offset:49152
	ds_read_b128 v[182:185], v211 offset:50176
	ds_read_b128 v[186:189], v211 offset:51200
	ds_read_b128 v[190:193], v211 offset:52224
	ds_read_b128 v[194:197], v211 offset:53248
	ds_read_b128 v[198:201], v211 offset:54272
	ds_read_b128 v[202:205], v211 offset:55296
	ds_read_b128 v[218:221], v211 offset:56320
	global_load_lds_dwordx4 v[206:207], off
	s_add_i32 m0, s50, 0x2000
	s_add_u32 s8, s8, 0x40080
	v_lshl_add_u64 v[206:207], v[222:223], 0, s[36:37]
	s_addc_u32 s9, s9, 0
	s_add_i32 s50, s80, s61
	global_load_lds_dwordx4 v[206:207], off
	v_lshl_add_u64 v[206:207], s[8:9], 0, v[162:163]
	s_mov_b32 m0, s50
	s_nop 0
	global_load_lds_dwordx4 v[206:207], off
	v_lshl_add_u64 v[206:207], s[8:9], 0, v[166:167]
	s_add_i32 m0, s50, 0x2000
	s_nop 0
	global_load_lds_dwordx4 v[206:207], off
	v_lshl_add_u64 v[206:207], v[224:225], 0, s[36:37]
	s_mov_b32 m0, s68
	s_nop 0
	global_load_lds_dwordx4 v[206:207], off
	v_lshl_add_u64 v[206:207], v[226:227], 0, s[36:37]
	s_mov_b32 m0, s69
	s_nop 0
	global_load_lds_dwordx4 v[206:207], off
	s_waitcnt vmcnt(8)
	s_waitcnt lgkmcnt(0)
	s_barrier
	s_setprio 1
	s_waitcnt lgkmcnt(0)
	v_mfma_f32_16x16x32_bf16 v[60:63], v[96:99], v[178:181], v[60:63]
	v_mfma_f32_16x16x32_bf16 v[56:59], v[120:123], v[178:181], v[56:59]
	v_mfma_f32_16x16x32_bf16 v[44:47], v[96:99], v[186:189], v[44:47]
	v_mfma_f32_16x16x32_bf16 v[40:43], v[120:123], v[186:189], v[40:43]
	v_mfma_f32_16x16x32_bf16 v[28:31], v[96:99], v[194:197], v[28:31]
	v_mfma_f32_16x16x32_bf16 v[24:27], v[120:123], v[194:197], v[24:27]
	v_mfma_f32_16x16x32_bf16 v[12:15], v[96:99], v[202:205], v[12:15]
	v_mfma_f32_16x16x32_bf16 v[8:11], v[120:123], v[202:205], v[8:11]
	v_mfma_f32_16x16x32_bf16 v[60:63], v[100:103], v[182:185], v[60:63]
	v_mfma_f32_16x16x32_bf16 v[56:59], v[124:127], v[182:185], v[56:59]
	v_mfma_f32_16x16x32_bf16 v[44:47], v[100:103], v[190:193], v[44:47]
	v_mfma_f32_16x16x32_bf16 v[40:43], v[124:127], v[190:193], v[40:43]
	v_mfma_f32_16x16x32_bf16 v[28:31], v[100:103], v[198:201], v[28:31]
	v_mfma_f32_16x16x32_bf16 v[24:27], v[124:127], v[198:201], v[24:27]
	v_mfma_f32_16x16x32_bf16 v[12:15], v[100:103], v[218:221], v[12:15]
	v_mfma_f32_16x16x32_bf16 v[8:11], v[124:127], v[218:221], v[8:11]
	s_setprio 0
	s_setprio 1
	v_mfma_f32_16x16x32_bf16 v[52:55], v[144:147], v[178:181], v[52:55]
	v_mfma_f32_16x16x32_bf16 v[48:51], v[152:155], v[178:181], v[48:51]
	v_mfma_f32_16x16x32_bf16 v[36:39], v[144:147], v[186:189], v[36:39]
	v_mfma_f32_16x16x32_bf16 v[32:35], v[152:155], v[186:189], v[32:35]
	v_mfma_f32_16x16x32_bf16 v[20:23], v[144:147], v[194:197], v[20:23]
	v_mfma_f32_16x16x32_bf16 v[16:19], v[152:155], v[194:197], v[16:19]
	v_mfma_f32_16x16x32_bf16 v[4:7], v[144:147], v[202:205], v[4:7]
	v_mfma_f32_16x16x32_bf16 v[0:3], v[152:155], v[202:205], v[0:3]
	s_setprio 2
	s_barrier
	v_mfma_f32_16x16x32_bf16 v[52:55], v[148:151], v[182:185], v[52:55]
	v_mfma_f32_16x16x32_bf16 v[48:51], v[156:159], v[182:185], v[48:51]
	v_mfma_f32_16x16x32_bf16 v[36:39], v[148:151], v[190:193], v[36:39]
	v_mfma_f32_16x16x32_bf16 v[32:35], v[156:159], v[190:193], v[32:35]
	v_mfma_f32_16x16x32_bf16 v[20:23], v[148:151], v[198:201], v[20:23]
	v_mfma_f32_16x16x32_bf16 v[16:19], v[156:159], v[198:201], v[16:19]
	v_mfma_f32_16x16x32_bf16 v[4:7], v[148:151], v[218:221], v[4:7]
	v_mfma_f32_16x16x32_bf16 v[0:3], v[156:159], v[218:221], v[0:3]
	s_setprio 0
	s_add_i32 s78, s78, 2
	s_add_u32 s6, s6, 0x100
	s_addc_u32 s7, s7, 0
	s_add_u32 s56, s56, 0x100
	s_addc_u32 s57, s57, 0
	s_cmp_gt_u32 s78, 13
	s_cbranch_scc0 .LBB0_323

.LBB0_697:
	s_and_b32 s29, s69, 0x1000
	s_add_i32 s70, s66, s29
	s_ashr_i32 s29, s28, 31
	ds_read_b128 v[0:3], v195 offset:3072
	ds_read_b128 v[4:7], v195 offset:2048
	ds_read_b128 v[8:11], v195 offset:1024
	ds_read_b128 v[12:15], v195
	ds_read_b128 v[16:19], v203 offset:3072
	ds_read_b128 v[20:23], v203 offset:2048
	ds_read_b128 v[24:27], v203 offset:1024
	ds_read_b128 v[28:31], v203
	s_lshl_b64 s[36:37], s[28:29], 20
	s_add_u32 s36, s50, s36
	s_addc_u32 s37, s51, s37
	s_and_b64 s[38:39], s[4:5], exec
	s_cselect_b32 s29, s37, s45
	s_cselect_b32 s71, s36, s44
	s_ashr_i32 s31, s30, 31
	s_lshl_b64 s[38:39], s[30:31], 20
	s_add_u32 s38, s54, s38
	s_addc_u32 s39, s55, s39
	s_and_b64 s[48:49], s[4:5], exec
	s_cselect_b32 s31, s39, s47
	s_cselect_b32 s72, s38, s46
	s_add_u32 s48, s44, 0x80080
	s_addc_u32 s49, s45, 0
	s_add_i32 s73, s56, 0xc000
	v_lshl_add_u64 v[64:65], s[48:49], 0, v[176:177]
	s_mov_b32 m0, s73
	s_add_i32 s74, s56, 0xe000
	ds_read_b128 v[32:35], v211
	ds_read_b128 v[36:39], v211 offset:1024
	ds_read_b128 v[40:43], v211 offset:2048
	ds_read_b128 v[44:47], v211 offset:3072
	ds_read_b128 v[48:51], v211 offset:4096
	ds_read_b128 v[52:55], v211 offset:5120
	ds_read_b128 v[56:59], v211 offset:6144
	ds_read_b128 v[60:63], v211 offset:7168
	global_load_lds_dwordx4 v[64:65], off
	v_lshl_add_u64 v[64:65], s[48:49], 0, v[178:179]
	s_mov_b32 m0, s74
	s_nop 0
	global_load_lds_dwordx4 v[64:65], off
	s_waitcnt vmcnt(8)
	s_waitcnt lgkmcnt(0)
	s_barrier
	s_setprio 1
	s_waitcnt lgkmcnt(0)
	v_mfma_f32_16x16x32_bf16 v[88:91], v[28:31], v[56:59], 0
	v_mfma_f32_16x16x32_bf16 v[64:67], v[28:31], v[32:35], 0
	v_mfma_f32_16x16x32_bf16 v[68:71], v[20:23], v[32:35], 0
	v_mfma_f32_16x16x32_bf16 v[72:75], v[28:31], v[40:43], 0
	v_mfma_f32_16x16x32_bf16 v[76:79], v[20:23], v[40:43], 0
	v_mfma_f32_16x16x32_bf16 v[80:83], v[28:31], v[48:51], 0
	v_mfma_f32_16x16x32_bf16 v[84:87], v[20:23], v[48:51], 0
	v_mfma_f32_16x16x32_bf16 v[96:99], v[24:27], v[60:63], v[88:91]
	v_mfma_f32_16x16x32_bf16 v[88:91], v[20:23], v[56:59], 0
	v_mfma_f32_16x16x32_bf16 v[64:67], v[24:27], v[36:39], v[64:67]
	v_mfma_f32_16x16x32_bf16 v[68:71], v[16:19], v[36:39], v[68:71]
	v_mfma_f32_16x16x32_bf16 v[72:75], v[24:27], v[44:47], v[72:75]
	v_mfma_f32_16x16x32_bf16 v[76:79], v[16:19], v[44:47], v[76:79]
	v_mfma_f32_16x16x32_bf16 v[80:83], v[24:27], v[52:55], v[80:83]
	v_mfma_f32_16x16x32_bf16 v[84:87], v[16:19], v[52:55], v[84:87]
	v_mfma_f32_16x16x32_bf16 v[100:103], v[16:19], v[60:63], v[88:91]
	s_setprio 0
	s_setprio 1
	v_mfma_f32_16x16x32_bf16 v[88:91], v[12:15], v[32:35], 0
	v_mfma_f32_16x16x32_bf16 v[32:35], v[4:7], v[32:35], 0
	v_mfma_f32_16x16x32_bf16 v[112:115], v[8:11], v[36:39], v[88:91]
	v_mfma_f32_16x16x32_bf16 v[32:35], v[0:3], v[36:39], v[32:35]
	v_mfma_f32_16x16x32_bf16 v[36:39], v[12:15], v[40:43], 0
	v_mfma_f32_16x16x32_bf16 v[40:43], v[4:7], v[40:43], 0
	v_mfma_f32_16x16x32_bf16 v[36:39], v[8:11], v[44:47], v[36:39]
	v_mfma_f32_16x16x32_bf16 v[40:43], v[0:3], v[44:47], v[40:43]
	s_setprio 2
	s_barrier
	v_mfma_f32_16x16x32_bf16 v[44:47], v[12:15], v[48:51], 0
	v_mfma_f32_16x16x32_bf16 v[48:51], v[4:7], v[48:51], 0
	v_mfma_f32_16x16x32_bf16 v[44:47], v[8:11], v[52:55], v[44:47]
	v_mfma_f32_16x16x32_bf16 v[48:51], v[0:3], v[52:55], v[48:51]
	v_mfma_f32_16x16x32_bf16 v[52:55], v[12:15], v[56:59], 0
	v_mfma_f32_16x16x32_bf16 v[56:59], v[4:7], v[56:59], 0
	v_mfma_f32_16x16x32_bf16 v[52:55], v[8:11], v[60:63], v[52:55]
	v_mfma_f32_16x16x32_bf16 v[56:59], v[0:3], v[60:63], v[56:59]
	s_setprio 0
	s_add_i32 s75, s68, s43
	v_lshl_add_u64 v[174:175], s[46:47], 0, v[176:177]
	s_add_i32 s76, s75, 0x2000
	v_lshl_add_u64 v[128:129], v[174:175], 0, s[24:25]
	s_mov_b32 m0, s75
	v_lshl_add_u64 v[200:201], s[46:47], 0, v[178:179]
	s_add_u32 s48, s46, 0x80100
	ds_read_b128 v[60:63], v211 offset:16384
	ds_read_b128 v[88:91], v211 offset:17408
	ds_read_b128 v[92:95], v211 offset:18432
	ds_read_b128 v[104:107], v211 offset:19456
	ds_read_b128 v[108:111], v211 offset:20480
	ds_read_b128 v[116:119], v211 offset:21504
	ds_read_b128 v[120:123], v211 offset:22528
	ds_read_b128 v[124:127], v211 offset:23552
	global_load_lds_dwordx4 v[128:129], off
	v_lshl_add_u64 v[128:129], v[200:201], 0, s[24:25]
	s_mov_b32 m0, s76
	s_addc_u32 s49, s47, 0
	s_add_i32 s77, s67, s43
	global_load_lds_dwordx4 v[128:129], off
	v_lshl_add_u64 v[128:129], s[48:49], 0, v[176:177]
	s_mov_b32 m0, s77
	s_add_i32 s78, s77, 0x2000
	global_load_lds_dwordx4 v[128:129], off
	v_lshl_add_u64 v[128:129], s[48:49], 0, v[178:179]
	s_mov_b32 m0, s78
	v_lshl_add_u64 v[208:209], s[44:45], 0, v[176:177]
	global_load_lds_dwordx4 v[128:129], off
	v_lshl_add_u64 v[128:129], v[208:209], 0, s[24:25]
	s_mov_b32 m0, s56
	v_lshl_add_u64 v[252:253], s[44:45], 0, v[178:179]
	global_load_lds_dwordx4 v[128:129], off
	v_lshl_add_u64 v[128:129], v[252:253], 0, s[24:25]
	s_mov_b32 m0, s57
	s_nop 0
	global_load_lds_dwordx4 v[128:129], off
	s_waitcnt vmcnt(8)
	s_waitcnt lgkmcnt(0)
	s_barrier
	s_setprio 1
	s_waitcnt lgkmcnt(0)
	v_mfma_f32_16x16x32_bf16 v[134:137], v[20:23], v[60:63], 0
	v_mfma_f32_16x16x32_bf16 v[142:145], v[20:23], v[92:95], 0
	v_mfma_f32_16x16x32_bf16 v[150:153], v[20:23], v[108:111], 0
	v_mfma_f32_16x16x32_bf16 v[20:23], v[20:23], v[120:123], 0
	v_mfma_f32_16x16x32_bf16 v[128:131], v[28:31], v[60:63], 0
	v_mfma_f32_16x16x32_bf16 v[134:137], v[16:19], v[88:91], v[134:137]
	v_mfma_f32_16x16x32_bf16 v[138:141], v[28:31], v[92:95], 0
	v_mfma_f32_16x16x32_bf16 v[142:145], v[16:19], v[104:107], v[142:145]
	v_mfma_f32_16x16x32_bf16 v[146:149], v[28:31], v[108:111], 0
	v_mfma_f32_16x16x32_bf16 v[150:153], v[16:19], v[116:119], v[150:153]
	v_mfma_f32_16x16x32_bf16 v[28:31], v[28:31], v[120:123], 0
	v_mfma_f32_16x16x32_bf16 v[16:19], v[16:19], v[124:127], v[20:23]
	v_mfma_f32_16x16x32_bf16 v[130:133], v[24:27], v[88:91], v[128:131]
	v_mfma_f32_16x16x32_bf16 v[138:141], v[24:27], v[104:107], v[138:141]
	v_mfma_f32_16x16x32_bf16 v[146:149], v[24:27], v[116:119], v[146:149]
	v_mfma_f32_16x16x32_bf16 v[154:157], v[24:27], v[124:127], v[28:31]
	s_setprio 0
	s_setprio 1
	v_mfma_f32_16x16x32_bf16 v[24:27], v[4:7], v[60:63], 0
	v_mfma_f32_16x16x32_bf16 v[158:161], v[0:3], v[88:91], v[24:27]
	v_mfma_f32_16x16x32_bf16 v[24:27], v[12:15], v[92:95], 0
	v_mfma_f32_16x16x32_bf16 v[162:165], v[8:11], v[104:107], v[24:27]
	v_mfma_f32_16x16x32_bf16 v[24:27], v[4:7], v[92:95], 0
	v_mfma_f32_16x16x32_bf16 v[166:169], v[0:3], v[104:107], v[24:27]
	v_mfma_f32_16x16x32_bf16 v[24:27], v[12:15], v[108:111], 0
	v_mfma_f32_16x16x32_bf16 v[20:23], v[12:15], v[60:63], 0
	s_setprio 2
	s_barrier
	v_mfma_f32_16x16x32_bf16 v[170:173], v[8:11], v[116:119], v[24:27]
	v_mfma_f32_16x16x32_bf16 v[24:27], v[4:7], v[108:111], 0
	v_mfma_f32_16x16x32_bf16 v[4:7], v[4:7], v[120:123], 0
	v_mfma_f32_16x16x32_bf16 v[20:23], v[8:11], v[88:91], v[20:23]
	v_mfma_f32_16x16x32_bf16 v[190:193], v[0:3], v[116:119], v[24:27]
	v_mfma_f32_16x16x32_bf16 v[12:15], v[12:15], v[120:123], 0
	v_mfma_f32_16x16x32_bf16 v[0:3], v[0:3], v[124:127], v[4:7]
	v_mfma_f32_16x16x32_bf16 v[196:199], v[8:11], v[124:127], v[12:15]
	s_setprio 0
	s_add_i32 s79, 0, 0x18000
	s_add_i32 s81, 0, 0x1c000
	v_add_u32_e32 v128, s79, v189
	v_add_u32_e32 v129, s81, v189
	ds_read_b128 v[4:7], v128
	ds_read_b128 v[8:11], v128 offset:1024
	ds_read_b128 v[204:207], v128 offset:2048
	ds_read_b128 v[212:215], v128 offset:3072
	ds_read_b128 v[216:219], v129
	ds_read_b128 v[220:223], v129 offset:1024
	ds_read_b128 v[224:227], v129 offset:2048
	ds_read_b128 v[228:231], v129 offset:3072
	s_add_u32 s48, s44, 0x80100
	s_addc_u32 s49, s45, 0
	s_mov_b32 m0, s58
	v_lshl_add_u64 v[88:89], s[48:49], 0, v[176:177]
	ds_read_b128 v[12:15], v211 offset:32768
	ds_read_b128 v[24:27], v211 offset:33792
	ds_read_b128 v[28:31], v211 offset:34816
	ds_read_b128 v[60:63], v211 offset:35840
	ds_read_b128 v[232:235], v211 offset:36864
	ds_read_b128 v[236:239], v211 offset:37888
	ds_read_b128 v[240:243], v211 offset:38912
	ds_read_b128 v[244:247], v211 offset:39936
	global_load_lds_dwordx4 v[88:89], off
	v_lshl_add_u64 v[88:89], s[48:49], 0, v[178:179]
	s_mov_b32 m0, s59
	s_nop 0
	global_load_lds_dwordx4 v[88:89], off
	s_waitcnt vmcnt(8)
	s_waitcnt lgkmcnt(0)
	s_barrier
	s_setprio 1
	s_waitcnt lgkmcnt(0)
	v_mfma_f32_16x16x32_bf16 v[64:67], v[4:7], v[12:15], v[64:67]
	v_mfma_f32_16x16x32_bf16 v[124:127], v[8:11], v[24:27], v[64:67]
	v_mfma_f32_16x16x32_bf16 v[64:67], v[204:207], v[12:15], v[68:71]
	v_mfma_f32_16x16x32_bf16 v[120:123], v[212:215], v[24:27], v[64:67]
	v_mfma_f32_16x16x32_bf16 v[64:67], v[4:7], v[28:31], v[72:75]
	v_mfma_f32_16x16x32_bf16 v[108:111], v[8:11], v[60:63], v[64:67]
	v_mfma_f32_16x16x32_bf16 v[64:67], v[204:207], v[28:31], v[76:79]
	v_mfma_f32_16x16x32_bf16 v[104:107], v[212:215], v[60:63], v[64:67]
	v_mfma_f32_16x16x32_bf16 v[64:67], v[4:7], v[232:235], v[80:83]
	v_mfma_f32_16x16x32_bf16 v[92:95], v[8:11], v[236:239], v[64:67]
	v_mfma_f32_16x16x32_bf16 v[64:67], v[204:207], v[232:235], v[84:87]
	v_mfma_f32_16x16x32_bf16 v[88:91], v[212:215], v[236:239], v[64:67]
	v_mfma_f32_16x16x32_bf16 v[64:67], v[4:7], v[240:243], v[96:99]
	v_mfma_f32_16x16x32_bf16 v[76:79], v[8:11], v[244:247], v[64:67]
	v_mfma_f32_16x16x32_bf16 v[64:67], v[204:207], v[240:243], v[100:103]
	v_mfma_f32_16x16x32_bf16 v[72:75], v[212:215], v[244:247], v[64:67]
	s_setprio 0
	s_setprio 1
	v_mfma_f32_16x16x32_bf16 v[64:67], v[216:219], v[12:15], v[112:115]
	v_mfma_f32_16x16x32_bf16 v[12:15], v[224:227], v[12:15], v[32:35]
	v_mfma_f32_16x16x32_bf16 v[112:115], v[228:231], v[24:27], v[12:15]
	v_mfma_f32_16x16x32_bf16 v[12:15], v[216:219], v[28:31], v[36:39]
	v_mfma_f32_16x16x32_bf16 v[100:103], v[220:223], v[60:63], v[12:15]
	v_mfma_f32_16x16x32_bf16 v[12:15], v[224:227], v[28:31], v[40:43]
	v_mfma_f32_16x16x32_bf16 v[96:99], v[228:231], v[60:63], v[12:15]
	v_mfma_f32_16x16x32_bf16 v[12:15], v[216:219], v[232:235], v[44:47]
	s_setprio 2
	s_barrier
	v_mfma_f32_16x16x32_bf16 v[84:87], v[220:223], v[236:239], v[12:15]
	v_mfma_f32_16x16x32_bf16 v[12:15], v[224:227], v[232:235], v[48:51]
	v_mfma_f32_16x16x32_bf16 v[80:83], v[228:231], v[236:239], v[12:15]
	v_mfma_f32_16x16x32_bf16 v[12:15], v[216:219], v[240:243], v[52:55]
	v_mfma_f32_16x16x32_bf16 v[68:71], v[220:223], v[244:247], v[12:15]
	v_mfma_f32_16x16x32_bf16 v[12:15], v[224:227], v[240:243], v[56:59]
	v_mfma_f32_16x16x32_bf16 v[116:119], v[220:223], v[24:27], v[64:67]
	v_mfma_f32_16x16x32_bf16 v[64:67], v[228:231], v[244:247], v[12:15]
	s_setprio 0
	s_add_i32 s79, s79, s43
	s_add_i32 s80, s79, 0x2000
	s_nop 1
	v_lshl_add_u64 v[12:13], v[174:175], 0, s[26:27]
	s_mov_b32 m0, s79
	s_add_u32 s48, s46, 0x80180
	ds_read_b128 v[32:35], v211 offset:49152
	ds_read_b128 v[36:39], v211 offset:50176
	ds_read_b128 v[232:235], v211 offset:51200
	ds_read_b128 v[236:239], v211 offset:52224
	ds_read_b128 v[240:243], v211 offset:53248
	ds_read_b128 v[244:247], v211 offset:54272
	ds_read_b128 v[248:251], v211 offset:55296
	ds_read_b128 v[184:187], v211 offset:56320
	global_load_lds_dwordx4 v[12:13], off
	v_lshl_add_u64 v[12:13], v[200:201], 0, s[26:27]
	s_mov_b32 m0, s80
	s_addc_u32 s49, s47, 0
	s_add_i32 s81, s81, s43
	global_load_lds_dwordx4 v[12:13], off
	v_lshl_add_u64 v[12:13], s[48:49], 0, v[176:177]
	s_mov_b32 m0, s81
	s_add_i32 s82, s81, 0x2000
	global_load_lds_dwordx4 v[12:13], off
	v_lshl_add_u64 v[12:13], s[48:49], 0, v[178:179]
	s_mov_b32 m0, s82
	s_nop 0
	global_load_lds_dwordx4 v[12:13], off
	v_lshl_add_u64 v[12:13], v[208:209], 0, s[26:27]
	s_mov_b32 m0, s61
	s_nop 0
	global_load_lds_dwordx4 v[12:13], off
	v_lshl_add_u64 v[12:13], v[252:253], 0, s[26:27]
	s_mov_b32 m0, s62
	s_nop 0
	global_load_lds_dwordx4 v[12:13], off
	s_waitcnt vmcnt(8)
	s_waitcnt lgkmcnt(0)
	s_barrier
	s_setprio 1
	s_waitcnt lgkmcnt(0)
	v_mfma_f32_16x16x32_bf16 v[12:15], v[4:7], v[32:35], v[130:133]
	v_mfma_f32_16x16x32_bf16 v[60:63], v[8:11], v[36:39], v[12:15]
	v_mfma_f32_16x16x32_bf16 v[12:15], v[204:207], v[32:35], v[134:137]
	v_mfma_f32_16x16x32_bf16 v[56:59], v[212:215], v[36:39], v[12:15]
	v_mfma_f32_16x16x32_bf16 v[12:15], v[4:7], v[232:235], v[138:141]
	v_mfma_f32_16x16x32_bf16 v[44:47], v[8:11], v[236:239], v[12:15]
	v_mfma_f32_16x16x32_bf16 v[12:15], v[204:207], v[232:235], v[142:145]
	v_mfma_f32_16x16x32_bf16 v[40:43], v[212:215], v[236:239], v[12:15]
	v_mfma_f32_16x16x32_bf16 v[12:15], v[4:7], v[240:243], v[146:149]
	v_mfma_f32_16x16x32_bf16 v[28:31], v[8:11], v[244:247], v[12:15]
	v_mfma_f32_16x16x32_bf16 v[12:15], v[204:207], v[240:243], v[150:153]
	v_mfma_f32_16x16x32_bf16 v[4:7], v[4:7], v[248:251], v[154:157]
	v_mfma_f32_16x16x32_bf16 v[24:27], v[212:215], v[244:247], v[12:15]
	v_mfma_f32_16x16x32_bf16 v[12:15], v[8:11], v[184:187], v[4:7]
	v_mfma_f32_16x16x32_bf16 v[4:7], v[204:207], v[248:251], v[16:19]
	v_mfma_f32_16x16x32_bf16 v[8:11], v[212:215], v[184:187], v[4:7]
	s_setprio 0
	s_setprio 1
	v_mfma_f32_16x16x32_bf16 v[4:7], v[216:219], v[32:35], v[20:23]
	v_mfma_f32_16x16x32_bf16 v[52:55], v[220:223], v[36:39], v[4:7]
	v_mfma_f32_16x16x32_bf16 v[4:7], v[224:227], v[32:35], v[158:161]
	v_mfma_f32_16x16x32_bf16 v[48:51], v[228:231], v[36:39], v[4:7]
	v_mfma_f32_16x16x32_bf16 v[4:7], v[216:219], v[232:235], v[162:165]
	v_mfma_f32_16x16x32_bf16 v[36:39], v[220:223], v[236:239], v[4:7]
	v_mfma_f32_16x16x32_bf16 v[4:7], v[224:227], v[232:235], v[166:169]
	v_mfma_f32_16x16x32_bf16 v[32:35], v[228:231], v[236:239], v[4:7]
	s_setprio 2
	s_barrier
	v_mfma_f32_16x16x32_bf16 v[4:7], v[216:219], v[240:243], v[170:173]
	v_mfma_f32_16x16x32_bf16 v[20:23], v[220:223], v[244:247], v[4:7]
	v_mfma_f32_16x16x32_bf16 v[4:7], v[224:227], v[240:243], v[190:193]
	v_mfma_f32_16x16x32_bf16 v[16:19], v[228:231], v[244:247], v[4:7]
	v_mfma_f32_16x16x32_bf16 v[4:7], v[216:219], v[248:251], v[196:199]
	v_mfma_f32_16x16x32_bf16 v[0:3], v[224:227], v[248:251], v[0:3]
	v_mfma_f32_16x16x32_bf16 v[4:7], v[220:223], v[184:187], v[4:7]
	v_mfma_f32_16x16x32_bf16 v[0:3], v[228:231], v[184:187], v[0:3]
	s_setprio 0
	s_add_u32 s44, s44, 0x80180
	s_addc_u32 s45, s45, 0
	s_add_u32 s83, s46, 0x200
	s_addc_u32 s84, s47, 0
	s_mov_b32 s46, 0
	s_add_i32 s85, s46, 2
	s_and_b32 s47, s85, 6
	s_cmp_lg_u32 s47, 0
	s_cbranch_scc1 .LBB0_700
	s_branch .LBB0_699

.LBB0_700:
	ds_read_b128 v[130:133], v203
	ds_read_b128 v[134:137], v203 offset:1024
	ds_read_b128 v[138:141], v203 offset:2048
	ds_read_b128 v[142:145], v203 offset:3072
	ds_read_b128 v[146:149], v195
	ds_read_b128 v[150:153], v195 offset:1024
	ds_read_b128 v[154:157], v195 offset:2048
	ds_read_b128 v[158:161], v195 offset:3072
	s_add_u32 s47, s44, 0xfff80080
	s_addc_u32 s48, s45, -1
	s_cmp_eq_u32 s46, 28
	s_cselect_b32 s49, s29, s48
	s_cselect_b32 s48, s71, s47
	s_cselect_b32 s47, s31, s84
	s_cselect_b32 s46, s72, s83
	s_mov_b32 m0, s73
	v_lshl_add_u64 v[174:175], s[44:45], 0, v[180:181]
	ds_read_b128 v[162:165], v211
	ds_read_b128 v[166:169], v211 offset:1024
	ds_read_b128 v[170:173], v211 offset:2048
	ds_read_b128 v[184:187], v211 offset:3072
	ds_read_b128 v[190:193], v211 offset:4096
	ds_read_b128 v[196:199], v211 offset:5120
	ds_read_b128 v[204:207], v211 offset:6144
	ds_read_b128 v[212:215], v211 offset:7168
	global_load_lds_dwordx4 v[174:175], off
	v_lshl_add_u64 v[174:175], s[44:45], 0, v[182:183]
	s_mov_b32 m0, s74
	s_nop 0
	global_load_lds_dwordx4 v[174:175], off
	s_waitcnt vmcnt(8)
	s_waitcnt lgkmcnt(0)
	s_barrier
	s_setprio 1
	s_waitcnt lgkmcnt(0)
	v_mfma_f32_16x16x32_bf16 v[124:127], v[130:133], v[162:165], v[124:127]
	v_mfma_f32_16x16x32_bf16 v[120:123], v[138:141], v[162:165], v[120:123]
	v_mfma_f32_16x16x32_bf16 v[108:111], v[130:133], v[170:173], v[108:111]
	v_mfma_f32_16x16x32_bf16 v[104:107], v[138:141], v[170:173], v[104:107]
	v_mfma_f32_16x16x32_bf16 v[92:95], v[130:133], v[190:193], v[92:95]
	v_mfma_f32_16x16x32_bf16 v[88:91], v[138:141], v[190:193], v[88:91]
	v_mfma_f32_16x16x32_bf16 v[76:79], v[130:133], v[204:207], v[76:79]
	v_mfma_f32_16x16x32_bf16 v[72:75], v[138:141], v[204:207], v[72:75]
	v_mfma_f32_16x16x32_bf16 v[124:127], v[134:137], v[166:169], v[124:127]
	v_mfma_f32_16x16x32_bf16 v[120:123], v[142:145], v[166:169], v[120:123]
	v_mfma_f32_16x16x32_bf16 v[108:111], v[134:137], v[184:187], v[108:111]
	v_mfma_f32_16x16x32_bf16 v[104:107], v[142:145], v[184:187], v[104:107]
	v_mfma_f32_16x16x32_bf16 v[92:95], v[134:137], v[196:199], v[92:95]
	v_mfma_f32_16x16x32_bf16 v[88:91], v[142:145], v[196:199], v[88:91]
	v_mfma_f32_16x16x32_bf16 v[76:79], v[134:137], v[212:215], v[76:79]
	v_mfma_f32_16x16x32_bf16 v[72:75], v[142:145], v[212:215], v[72:75]
	s_setprio 0
	s_setprio 1
	v_mfma_f32_16x16x32_bf16 v[116:119], v[146:149], v[162:165], v[116:119]
	v_mfma_f32_16x16x32_bf16 v[112:115], v[154:157], v[162:165], v[112:115]
	v_mfma_f32_16x16x32_bf16 v[100:103], v[146:149], v[170:173], v[100:103]
	v_mfma_f32_16x16x32_bf16 v[96:99], v[154:157], v[170:173], v[96:99]
	v_mfma_f32_16x16x32_bf16 v[84:87], v[146:149], v[190:193], v[84:87]
	v_mfma_f32_16x16x32_bf16 v[80:83], v[154:157], v[190:193], v[80:83]
	v_mfma_f32_16x16x32_bf16 v[68:71], v[146:149], v[204:207], v[68:71]
	v_mfma_f32_16x16x32_bf16 v[64:67], v[154:157], v[204:207], v[64:67]
	s_setprio 2
	s_barrier
	v_mfma_f32_16x16x32_bf16 v[116:119], v[150:153], v[166:169], v[116:119]
	v_mfma_f32_16x16x32_bf16 v[112:115], v[158:161], v[166:169], v[112:115]
	v_mfma_f32_16x16x32_bf16 v[100:103], v[150:153], v[184:187], v[100:103]
	v_mfma_f32_16x16x32_bf16 v[96:99], v[158:161], v[184:187], v[96:99]
	v_mfma_f32_16x16x32_bf16 v[84:87], v[150:153], v[196:199], v[84:87]
	v_mfma_f32_16x16x32_bf16 v[80:83], v[158:161], v[196:199], v[80:83]
	v_mfma_f32_16x16x32_bf16 v[68:71], v[150:153], v[212:215], v[68:71]
	v_mfma_f32_16x16x32_bf16 v[64:67], v[158:161], v[212:215], v[64:67]
	s_setprio 0
	s_mov_b32 m0, s75
	v_lshl_add_u64 v[174:175], s[46:47], 0, v[176:177]
	s_add_u32 s86, s46, 0x80000
	ds_read_b128 v[162:165], v211 offset:16384
	ds_read_b128 v[166:169], v211 offset:17408
	ds_read_b128 v[170:173], v211 offset:18432
	ds_read_b128 v[184:187], v211 offset:19456
	ds_read_b128 v[190:193], v211 offset:20480
	ds_read_b128 v[196:199], v211 offset:21504
	ds_read_b128 v[204:207], v211 offset:22528
	ds_read_b128 v[212:215], v211 offset:23552
	global_load_lds_dwordx4 v[174:175], off
	v_lshl_add_u64 v[200:201], s[46:47], 0, v[178:179]
	s_mov_b32 m0, s76
	s_addc_u32 s87, s47, 0
	global_load_lds_dwordx4 v[200:201], off
	v_lshl_add_u64 v[208:209], s[86:87], 0, v[176:177]
	s_mov_b32 m0, s77
	v_lshl_add_u64 v[216:217], s[48:49], 0, v[178:179]
	global_load_lds_dwordx4 v[208:209], off
	v_lshl_add_u64 v[208:209], s[86:87], 0, v[178:179]
	s_mov_b32 m0, s78
	s_nop 0
	global_load_lds_dwordx4 v[208:209], off
	v_lshl_add_u64 v[208:209], s[48:49], 0, v[176:177]
	s_mov_b32 m0, s56
	s_nop 0
	global_load_lds_dwordx4 v[208:209], off
	s_mov_b32 m0, s57
	s_nop 0
	global_load_lds_dwordx4 v[216:217], off
	s_waitcnt vmcnt(8)
	s_waitcnt lgkmcnt(0)
	s_barrier
	s_setprio 1
	s_waitcnt lgkmcnt(0)
	v_mfma_f32_16x16x32_bf16 v[60:63], v[130:133], v[162:165], v[60:63]
	v_mfma_f32_16x16x32_bf16 v[56:59], v[138:141], v[162:165], v[56:59]
	v_mfma_f32_16x16x32_bf16 v[44:47], v[130:133], v[170:173], v[44:47]
	v_mfma_f32_16x16x32_bf16 v[40:43], v[138:141], v[170:173], v[40:43]
	v_mfma_f32_16x16x32_bf16 v[28:31], v[130:133], v[190:193], v[28:31]
	v_mfma_f32_16x16x32_bf16 v[24:27], v[138:141], v[190:193], v[24:27]
	v_mfma_f32_16x16x32_bf16 v[12:15], v[130:133], v[204:207], v[12:15]
	v_mfma_f32_16x16x32_bf16 v[8:11], v[138:141], v[204:207], v[8:11]
	v_mfma_f32_16x16x32_bf16 v[60:63], v[134:137], v[166:169], v[60:63]
	v_mfma_f32_16x16x32_bf16 v[56:59], v[142:145], v[166:169], v[56:59]
	v_mfma_f32_16x16x32_bf16 v[44:47], v[134:137], v[184:187], v[44:47]
	v_mfma_f32_16x16x32_bf16 v[40:43], v[142:145], v[184:187], v[40:43]
	v_mfma_f32_16x16x32_bf16 v[28:31], v[134:137], v[196:199], v[28:31]
	v_mfma_f32_16x16x32_bf16 v[24:27], v[142:145], v[196:199], v[24:27]
	v_mfma_f32_16x16x32_bf16 v[12:15], v[134:137], v[212:215], v[12:15]
	v_mfma_f32_16x16x32_bf16 v[8:11], v[142:145], v[212:215], v[8:11]
	s_setprio 0
	s_setprio 1
	v_mfma_f32_16x16x32_bf16 v[52:55], v[146:149], v[162:165], v[52:55]
	v_mfma_f32_16x16x32_bf16 v[48:51], v[154:157], v[162:165], v[48:51]
	v_mfma_f32_16x16x32_bf16 v[36:39], v[146:149], v[170:173], v[36:39]
	v_mfma_f32_16x16x32_bf16 v[32:35], v[154:157], v[170:173], v[32:35]
	v_mfma_f32_16x16x32_bf16 v[20:23], v[146:149], v[190:193], v[20:23]
	v_mfma_f32_16x16x32_bf16 v[16:19], v[154:157], v[190:193], v[16:19]
	v_mfma_f32_16x16x32_bf16 v[4:7], v[146:149], v[204:207], v[4:7]
	v_mfma_f32_16x16x32_bf16 v[0:3], v[154:157], v[204:207], v[0:3]
	s_setprio 2
	s_barrier
	v_mfma_f32_16x16x32_bf16 v[52:55], v[150:153], v[166:169], v[52:55]
	v_mfma_f32_16x16x32_bf16 v[48:51], v[158:161], v[166:169], v[48:51]
	v_mfma_f32_16x16x32_bf16 v[36:39], v[150:153], v[184:187], v[36:39]
	v_mfma_f32_16x16x32_bf16 v[32:35], v[158:161], v[184:187], v[32:35]
	v_mfma_f32_16x16x32_bf16 v[20:23], v[150:153], v[196:199], v[20:23]
	v_mfma_f32_16x16x32_bf16 v[16:19], v[158:161], v[196:199], v[16:19]
	v_mfma_f32_16x16x32_bf16 v[4:7], v[150:153], v[212:215], v[4:7]
	v_mfma_f32_16x16x32_bf16 v[0:3], v[158:161], v[212:215], v[0:3]
	s_setprio 0
	ds_read_b128 v[130:133], v128
	ds_read_b128 v[134:137], v128 offset:1024
	ds_read_b128 v[138:141], v128 offset:2048
	ds_read_b128 v[142:145], v128 offset:3072
	ds_read_b128 v[146:149], v129
	ds_read_b128 v[150:153], v129 offset:1024
	ds_read_b128 v[154:157], v129 offset:2048
	ds_read_b128 v[158:161], v129 offset:3072
	s_add_u32 s48, s48, 0x80000
	s_addc_u32 s49, s49, 0
	s_mov_b32 m0, s58
	v_lshl_add_u64 v[218:219], s[48:49], 0, v[176:177]
	ds_read_b128 v[162:165], v211 offset:32768
	ds_read_b128 v[166:169], v211 offset:33792
	ds_read_b128 v[170:173], v211 offset:34816
	ds_read_b128 v[184:187], v211 offset:35840
	ds_read_b128 v[190:193], v211 offset:36864
	ds_read_b128 v[196:199], v211 offset:37888
	ds_read_b128 v[204:207], v211 offset:38912
	ds_read_b128 v[212:215], v211 offset:39936
	global_load_lds_dwordx4 v[218:219], off
	v_lshl_add_u64 v[218:219], s[48:49], 0, v[178:179]
	s_mov_b32 m0, s59
	s_nop 0
	global_load_lds_dwordx4 v[218:219], off
	s_waitcnt vmcnt(8)
	s_waitcnt lgkmcnt(0)
	s_barrier
	s_setprio 1
	s_waitcnt lgkmcnt(0)
	v_mfma_f32_16x16x32_bf16 v[124:127], v[130:133], v[162:165], v[124:127]
	v_mfma_f32_16x16x32_bf16 v[120:123], v[138:141], v[162:165], v[120:123]
	v_mfma_f32_16x16x32_bf16 v[108:111], v[130:133], v[170:173], v[108:111]
	v_mfma_f32_16x16x32_bf16 v[104:107], v[138:141], v[170:173], v[104:107]
	v_mfma_f32_16x16x32_bf16 v[92:95], v[130:133], v[190:193], v[92:95]
	v_mfma_f32_16x16x32_bf16 v[88:91], v[138:141], v[190:193], v[88:91]
	v_mfma_f32_16x16x32_bf16 v[76:79], v[130:133], v[204:207], v[76:79]
	v_mfma_f32_16x16x32_bf16 v[72:75], v[138:141], v[204:207], v[72:75]
	v_mfma_f32_16x16x32_bf16 v[124:127], v[134:137], v[166:169], v[124:127]
	v_mfma_f32_16x16x32_bf16 v[120:123], v[142:145], v[166:169], v[120:123]
	v_mfma_f32_16x16x32_bf16 v[108:111], v[134:137], v[184:187], v[108:111]
	v_mfma_f32_16x16x32_bf16 v[104:107], v[142:145], v[184:187], v[104:107]
	v_mfma_f32_16x16x32_bf16 v[92:95], v[134:137], v[196:199], v[92:95]
	v_mfma_f32_16x16x32_bf16 v[88:91], v[142:145], v[196:199], v[88:91]
	v_mfma_f32_16x16x32_bf16 v[76:79], v[134:137], v[212:215], v[76:79]
	v_mfma_f32_16x16x32_bf16 v[72:75], v[142:145], v[212:215], v[72:75]
	s_setprio 0
	s_setprio 1
	v_mfma_f32_16x16x32_bf16 v[116:119], v[146:149], v[162:165], v[116:119]
	v_mfma_f32_16x16x32_bf16 v[112:115], v[154:157], v[162:165], v[112:115]
	v_mfma_f32_16x16x32_bf16 v[100:103], v[146:149], v[170:173], v[100:103]
	v_mfma_f32_16x16x32_bf16 v[96:99], v[154:157], v[170:173], v[96:99]
	v_mfma_f32_16x16x32_bf16 v[84:87], v[146:149], v[190:193], v[84:87]
	v_mfma_f32_16x16x32_bf16 v[80:83], v[154:157], v[190:193], v[80:83]
	v_mfma_f32_16x16x32_bf16 v[68:71], v[146:149], v[204:207], v[68:71]
	v_mfma_f32_16x16x32_bf16 v[64:67], v[154:157], v[204:207], v[64:67]
	s_setprio 2
	s_barrier
	v_mfma_f32_16x16x32_bf16 v[116:119], v[150:153], v[166:169], v[116:119]
	v_mfma_f32_16x16x32_bf16 v[112:115], v[158:161], v[166:169], v[112:115]
	v_mfma_f32_16x16x32_bf16 v[100:103], v[150:153], v[184:187], v[100:103]
	v_mfma_f32_16x16x32_bf16 v[96:99], v[158:161], v[184:187], v[96:99]
	v_mfma_f32_16x16x32_bf16 v[84:87], v[150:153], v[196:199], v[84:87]
	v_mfma_f32_16x16x32_bf16 v[80:83], v[158:161], v[196:199], v[80:83]
	v_mfma_f32_16x16x32_bf16 v[68:71], v[150:153], v[212:215], v[68:71]
	v_mfma_f32_16x16x32_bf16 v[64:67], v[158:161], v[212:215], v[64:67]
	s_setprio 0
	s_mov_b32 m0, s79
	v_lshl_add_u64 v[174:175], v[174:175], 0, s[20:21]
	s_add_u32 s46, s46, 0x80080
	ds_read_b128 v[162:165], v211 offset:49152
	ds_read_b128 v[166:169], v211 offset:50176
	ds_read_b128 v[170:173], v211 offset:51200
	ds_read_b128 v[184:187], v211 offset:52224
	ds_read_b128 v[190:193], v211 offset:53248
	ds_read_b128 v[196:199], v211 offset:54272
	ds_read_b128 v[204:207], v211 offset:55296
	ds_read_b128 v[212:215], v211 offset:56320
	global_load_lds_dwordx4 v[174:175], off
	v_lshl_add_u64 v[174:175], v[200:201], 0, s[20:21]
	s_mov_b32 m0, s80
	s_addc_u32 s47, s47, 0
	global_load_lds_dwordx4 v[174:175], off
	v_lshl_add_u64 v[174:175], s[46:47], 0, v[176:177]
	s_mov_b32 m0, s81
	s_nop 0
	global_load_lds_dwordx4 v[174:175], off
	v_lshl_add_u64 v[174:175], s[46:47], 0, v[178:179]
	s_mov_b32 m0, s82
	s_nop 0
	global_load_lds_dwordx4 v[174:175], off
	v_lshl_add_u64 v[174:175], v[208:209], 0, s[20:21]
	s_mov_b32 m0, s61
	s_nop 0
	global_load_lds_dwordx4 v[174:175], off
	v_lshl_add_u64 v[174:175], v[216:217], 0, s[20:21]
	s_mov_b32 m0, s62
	s_nop 0
	global_load_lds_dwordx4 v[174:175], off
	s_waitcnt vmcnt(8)
	s_waitcnt lgkmcnt(0)
	s_barrier
	s_setprio 1
	s_waitcnt lgkmcnt(0)
	v_mfma_f32_16x16x32_bf16 v[60:63], v[130:133], v[162:165], v[60:63]
	v_mfma_f32_16x16x32_bf16 v[56:59], v[138:141], v[162:165], v[56:59]
	v_mfma_f32_16x16x32_bf16 v[44:47], v[130:133], v[170:173], v[44:47]
	v_mfma_f32_16x16x32_bf16 v[40:43], v[138:141], v[170:173], v[40:43]
	v_mfma_f32_16x16x32_bf16 v[28:31], v[130:133], v[190:193], v[28:31]
	v_mfma_f32_16x16x32_bf16 v[24:27], v[138:141], v[190:193], v[24:27]
	v_mfma_f32_16x16x32_bf16 v[12:15], v[130:133], v[204:207], v[12:15]
	v_mfma_f32_16x16x32_bf16 v[8:11], v[138:141], v[204:207], v[8:11]
	v_mfma_f32_16x16x32_bf16 v[60:63], v[134:137], v[166:169], v[60:63]
	v_mfma_f32_16x16x32_bf16 v[56:59], v[142:145], v[166:169], v[56:59]
	v_mfma_f32_16x16x32_bf16 v[44:47], v[134:137], v[184:187], v[44:47]
	v_mfma_f32_16x16x32_bf16 v[40:43], v[142:145], v[184:187], v[40:43]
	v_mfma_f32_16x16x32_bf16 v[28:31], v[134:137], v[196:199], v[28:31]
	v_mfma_f32_16x16x32_bf16 v[24:27], v[142:145], v[196:199], v[24:27]
	v_mfma_f32_16x16x32_bf16 v[12:15], v[134:137], v[212:215], v[12:15]
	v_mfma_f32_16x16x32_bf16 v[8:11], v[142:145], v[212:215], v[8:11]
	s_setprio 0
	s_setprio 1
	v_mfma_f32_16x16x32_bf16 v[52:55], v[146:149], v[162:165], v[52:55]
	v_mfma_f32_16x16x32_bf16 v[48:51], v[154:157], v[162:165], v[48:51]
	v_mfma_f32_16x16x32_bf16 v[36:39], v[146:149], v[170:173], v[36:39]
	v_mfma_f32_16x16x32_bf16 v[32:35], v[154:157], v[170:173], v[32:35]
	v_mfma_f32_16x16x32_bf16 v[20:23], v[146:149], v[190:193], v[20:23]
	v_mfma_f32_16x16x32_bf16 v[16:19], v[154:157], v[190:193], v[16:19]
	v_mfma_f32_16x16x32_bf16 v[4:7], v[146:149], v[204:207], v[4:7]
	v_mfma_f32_16x16x32_bf16 v[0:3], v[154:157], v[204:207], v[0:3]
	s_setprio 2
	s_barrier
	v_mfma_f32_16x16x32_bf16 v[52:55], v[150:153], v[166:169], v[52:55]
	v_mfma_f32_16x16x32_bf16 v[48:51], v[158:161], v[166:169], v[48:51]
	v_mfma_f32_16x16x32_bf16 v[36:39], v[150:153], v[184:187], v[36:39]
	v_mfma_f32_16x16x32_bf16 v[32:35], v[158:161], v[184:187], v[32:35]
	v_mfma_f32_16x16x32_bf16 v[20:23], v[150:153], v[196:199], v[20:23]
	v_mfma_f32_16x16x32_bf16 v[16:19], v[158:161], v[196:199], v[16:19]
	v_mfma_f32_16x16x32_bf16 v[4:7], v[150:153], v[212:215], v[4:7]
	v_mfma_f32_16x16x32_bf16 v[0:3], v[158:161], v[212:215], v[0:3]
	s_setprio 0
	s_add_i32 s70, s70, 1
	s_add_u32 s44, s44, 0x100
	s_addc_u32 s45, s45, 0
	s_add_u32 s83, s83, 0x100
	s_addc_u32 s84, s84, 0
	s_cmp_gt_u32 s85, 29
	s_cbranch_scc0 .LBB0_698
	s_lshl_b32 s29, s41, 12
	s_and_b32 s29, s29, 0x1000
	s_add_i32 s29, s29, 0
	v_mbcnt_lo_u32_b32 v128, -1, 0
	v_mbcnt_hi_u32_b32 v128, -1, v128
	s_add_i32 s29, s29, s63
	v_lshlrev_b32_e32 v128, 4, v128
	s_add_i32 s29, s29, 0x20400
	v_and_b32_e32 v128, 0xf0, v128
	v_add_u32_e32 v128, s29, v128
	ds_read2_b32 v[214:215], v128 offset0:3 offset1:67
	ds_read2_b32 v[206:207], v128 offset0:131 offset1:195
	v_add_u32_e32 v128, 12, v128
	ds_read2st64_b32 v[196:197], v128 offset0:8 offset1:9
	ds_read2st64_b32 v[190:191], v128 offset0:10 offset1:11
	s_and_b64 vcc, exec, s[22:23]
	s_waitcnt lgkmcnt(0)
	v_mov_b32_e32 v210, v215
	v_mov_b32_e32 v202, v207
	v_mov_b32_e32 v194, v197
	v_mov_b32_e32 v188, v191
	s_cbranch_vccz .LBB0_703
	s_barrier

.LBB0_784:
	ds_read_b128 v[144:147], v163
	ds_read_b128 v[148:151], v163 offset:1024
	ds_read_b128 v[152:155], v163 offset:2048
	ds_read_b128 v[156:159], v163 offset:3072
	ds_read_b128 v[168:171], v164
	ds_read_b128 v[172:175], v164 offset:1024
	ds_read_b128 v[176:179], v164 offset:2048
	ds_read_b128 v[180:183], v164 offset:3072
	s_add_u32 s38, s36, 0xfffc0080
	s_addc_u32 s39, s37, -1
	s_cmp_eq_u32 s65, 12
	s_cselect_b32 s41, s23, s39
	s_cselect_b32 s40, s31, s38
	s_cselect_b32 s39, s25, s64
	s_cselect_b32 s38, s62, s63
	v_lshl_add_u64 v[160:161], s[36:37], 0, v[136:137]
	s_add_i32 m0, s50, 0xc000
	ds_read_b128 v[184:187], v165
	ds_read_b128 v[188:191], v165 offset:1024
	ds_read_b128 v[192:195], v165 offset:2048
	ds_read_b128 v[196:199], v165 offset:3072
	ds_read_b128 v[200:203], v165 offset:4096
	ds_read_b128 v[204:207], v165 offset:5120
	ds_read_b128 v[208:211], v165 offset:6144
	ds_read_b128 v[212:215], v165 offset:7168
	global_load_lds_dwordx4 v[160:161], off
	v_lshl_add_u64 v[160:161], s[36:37], 0, v[138:139]
	s_add_i32 m0, s50, 0xe000
	s_nop 0
	global_load_lds_dwordx4 v[160:161], off
	s_waitcnt vmcnt(8)
	s_waitcnt lgkmcnt(0)
	s_barrier
	s_setprio 1
	s_waitcnt lgkmcnt(0)
	v_mfma_f32_16x16x32_bf16 v[124:127], v[144:147], v[184:187], v[124:127]
	v_mfma_f32_16x16x32_bf16 v[120:123], v[152:155], v[184:187], v[120:123]
	v_mfma_f32_16x16x32_bf16 v[108:111], v[144:147], v[192:195], v[108:111]
	v_mfma_f32_16x16x32_bf16 v[104:107], v[152:155], v[192:195], v[104:107]
	v_mfma_f32_16x16x32_bf16 v[92:95], v[144:147], v[200:203], v[92:95]
	v_mfma_f32_16x16x32_bf16 v[88:91], v[152:155], v[200:203], v[88:91]
	v_mfma_f32_16x16x32_bf16 v[76:79], v[144:147], v[208:211], v[76:79]
	v_mfma_f32_16x16x32_bf16 v[72:75], v[152:155], v[208:211], v[72:75]
	v_mfma_f32_16x16x32_bf16 v[124:127], v[148:151], v[188:191], v[124:127]
	v_mfma_f32_16x16x32_bf16 v[120:123], v[156:159], v[188:191], v[120:123]
	v_mfma_f32_16x16x32_bf16 v[108:111], v[148:151], v[196:199], v[108:111]
	v_mfma_f32_16x16x32_bf16 v[104:107], v[156:159], v[196:199], v[104:107]
	v_mfma_f32_16x16x32_bf16 v[92:95], v[148:151], v[204:207], v[92:95]
	v_mfma_f32_16x16x32_bf16 v[88:91], v[156:159], v[204:207], v[88:91]
	v_mfma_f32_16x16x32_bf16 v[76:79], v[148:151], v[212:215], v[76:79]
	v_mfma_f32_16x16x32_bf16 v[72:75], v[156:159], v[212:215], v[72:75]
	s_setprio 0
	s_setprio 1
	v_mfma_f32_16x16x32_bf16 v[116:119], v[168:171], v[184:187], v[116:119]
	v_mfma_f32_16x16x32_bf16 v[112:115], v[176:179], v[184:187], v[112:115]
	v_mfma_f32_16x16x32_bf16 v[100:103], v[168:171], v[192:195], v[100:103]
	v_mfma_f32_16x16x32_bf16 v[96:99], v[176:179], v[192:195], v[96:99]
	v_mfma_f32_16x16x32_bf16 v[84:87], v[168:171], v[200:203], v[84:87]
	v_mfma_f32_16x16x32_bf16 v[80:83], v[176:179], v[200:203], v[80:83]
	v_mfma_f32_16x16x32_bf16 v[68:71], v[168:171], v[208:211], v[68:71]
	v_mfma_f32_16x16x32_bf16 v[64:67], v[176:179], v[208:211], v[64:67]
	s_setprio 2
	s_barrier
	v_mfma_f32_16x16x32_bf16 v[116:119], v[172:175], v[188:191], v[116:119]
	v_mfma_f32_16x16x32_bf16 v[112:115], v[180:183], v[188:191], v[112:115]
	v_mfma_f32_16x16x32_bf16 v[100:103], v[172:175], v[196:199], v[100:103]
	v_mfma_f32_16x16x32_bf16 v[96:99], v[180:183], v[196:199], v[96:99]
	v_mfma_f32_16x16x32_bf16 v[84:87], v[172:175], v[204:207], v[84:87]
	v_mfma_f32_16x16x32_bf16 v[80:83], v[180:183], v[204:207], v[80:83]
	v_mfma_f32_16x16x32_bf16 v[68:71], v[172:175], v[212:215], v[68:71]
	v_mfma_f32_16x16x32_bf16 v[64:67], v[180:183], v[212:215], v[64:67]
	s_setprio 0
	s_add_i32 s66, s59, s47
	v_lshl_add_u64 v[160:161], s[38:39], 0, v[132:133]
	s_mov_b32 m0, s66
	ds_read_b128 v[184:187], v165 offset:16384
	ds_read_b128 v[188:191], v165 offset:17408
	ds_read_b128 v[192:195], v165 offset:18432
	ds_read_b128 v[196:199], v165 offset:19456
	ds_read_b128 v[200:203], v165 offset:20480
	ds_read_b128 v[204:207], v165 offset:21504
	ds_read_b128 v[208:211], v165 offset:22528
	ds_read_b128 v[212:215], v165 offset:23552
	global_load_lds_dwordx4 v[160:161], off
	s_add_i32 m0, s66, 0x2000
	s_add_u32 s66, s38, 0x40000
	v_lshl_add_u64 v[216:217], s[38:39], 0, v[128:129]
	s_addc_u32 s67, s39, 0
	s_add_i32 s68, s60, s47
	global_load_lds_dwordx4 v[216:217], off
	v_lshl_add_u64 v[218:219], s[66:67], 0, v[132:133]
	s_mov_b32 m0, s68
	v_lshl_add_u64 v[220:221], s[40:41], 0, v[130:131]
	global_load_lds_dwordx4 v[218:219], off
	v_lshl_add_u64 v[218:219], s[66:67], 0, v[128:129]
	s_add_i32 m0, s68, 0x2000
	s_nop 0
	global_load_lds_dwordx4 v[218:219], off
	v_lshl_add_u64 v[218:219], s[40:41], 0, v[134:135]
	s_mov_b32 m0, s50
	s_nop 0
	global_load_lds_dwordx4 v[218:219], off
	s_mov_b32 m0, s51
	s_nop 0
	global_load_lds_dwordx4 v[220:221], off
	s_waitcnt vmcnt(8)
	s_waitcnt lgkmcnt(0)
	s_barrier
	s_setprio 1
	s_waitcnt lgkmcnt(0)
	v_mfma_f32_16x16x32_bf16 v[60:63], v[144:147], v[184:187], v[60:63]
	v_mfma_f32_16x16x32_bf16 v[56:59], v[152:155], v[184:187], v[56:59]
	v_mfma_f32_16x16x32_bf16 v[44:47], v[144:147], v[192:195], v[44:47]
	v_mfma_f32_16x16x32_bf16 v[40:43], v[152:155], v[192:195], v[40:43]
	v_mfma_f32_16x16x32_bf16 v[28:31], v[144:147], v[200:203], v[28:31]
	v_mfma_f32_16x16x32_bf16 v[24:27], v[152:155], v[200:203], v[24:27]
	v_mfma_f32_16x16x32_bf16 v[12:15], v[144:147], v[208:211], v[12:15]
	v_mfma_f32_16x16x32_bf16 v[8:11], v[152:155], v[208:211], v[8:11]
	v_mfma_f32_16x16x32_bf16 v[60:63], v[148:151], v[188:191], v[60:63]
	v_mfma_f32_16x16x32_bf16 v[56:59], v[156:159], v[188:191], v[56:59]
	v_mfma_f32_16x16x32_bf16 v[44:47], v[148:151], v[196:199], v[44:47]
	v_mfma_f32_16x16x32_bf16 v[40:43], v[156:159], v[196:199], v[40:43]
	v_mfma_f32_16x16x32_bf16 v[28:31], v[148:151], v[204:207], v[28:31]
	v_mfma_f32_16x16x32_bf16 v[24:27], v[156:159], v[204:207], v[24:27]
	v_mfma_f32_16x16x32_bf16 v[12:15], v[148:151], v[212:215], v[12:15]
	v_mfma_f32_16x16x32_bf16 v[8:11], v[156:159], v[212:215], v[8:11]
	s_setprio 0
	s_setprio 1
	v_mfma_f32_16x16x32_bf16 v[52:55], v[168:171], v[184:187], v[52:55]
	v_mfma_f32_16x16x32_bf16 v[48:51], v[176:179], v[184:187], v[48:51]
	v_mfma_f32_16x16x32_bf16 v[36:39], v[168:171], v[192:195], v[36:39]
	v_mfma_f32_16x16x32_bf16 v[32:35], v[176:179], v[192:195], v[32:35]
	v_mfma_f32_16x16x32_bf16 v[20:23], v[168:171], v[200:203], v[20:23]
	v_mfma_f32_16x16x32_bf16 v[16:19], v[176:179], v[200:203], v[16:19]
	v_mfma_f32_16x16x32_bf16 v[4:7], v[168:171], v[208:211], v[4:7]
	v_mfma_f32_16x16x32_bf16 v[0:3], v[176:179], v[208:211], v[0:3]
	s_setprio 2
	s_barrier
	v_mfma_f32_16x16x32_bf16 v[52:55], v[172:175], v[188:191], v[52:55]
	v_mfma_f32_16x16x32_bf16 v[48:51], v[180:183], v[188:191], v[48:51]
	v_mfma_f32_16x16x32_bf16 v[36:39], v[172:175], v[196:199], v[36:39]
	v_mfma_f32_16x16x32_bf16 v[32:35], v[180:183], v[196:199], v[32:35]
	v_mfma_f32_16x16x32_bf16 v[20:23], v[172:175], v[204:207], v[20:23]
	v_mfma_f32_16x16x32_bf16 v[16:19], v[180:183], v[204:207], v[16:19]
	v_mfma_f32_16x16x32_bf16 v[4:7], v[172:175], v[212:215], v[4:7]
	v_mfma_f32_16x16x32_bf16 v[0:3], v[180:183], v[212:215], v[0:3]
	s_setprio 0
	s_add_i32 s66, 0, 0x18000
	s_add_i32 s67, 0, 0x1c000
	v_add_u32_e32 v156, s66, v162
	v_add_u32_e32 v167, s67, v162
	ds_read_b128 v[144:147], v156
	ds_read_b128 v[148:151], v156 offset:1024
	ds_read_b128 v[152:155], v156 offset:2048
	ds_read_b128 v[156:159], v156 offset:3072
	ds_read_b128 v[168:171], v167
	ds_read_b128 v[172:175], v167 offset:1024
	ds_read_b128 v[176:179], v167 offset:2048
	ds_read_b128 v[180:183], v167 offset:3072
	s_add_u32 s40, s40, 0x40000
	s_addc_u32 s41, s41, 0
	s_mov_b32 m0, s54
	v_lshl_add_u64 v[222:223], s[40:41], 0, v[134:135]
	ds_read_b128 v[184:187], v165 offset:32768
	ds_read_b128 v[188:191], v165 offset:33792
	ds_read_b128 v[192:195], v165 offset:34816
	ds_read_b128 v[196:199], v165 offset:35840
	ds_read_b128 v[200:203], v165 offset:36864
	ds_read_b128 v[204:207], v165 offset:37888
	ds_read_b128 v[208:211], v165 offset:38912
	ds_read_b128 v[212:215], v165 offset:39936
	global_load_lds_dwordx4 v[222:223], off
	v_lshl_add_u64 v[222:223], s[40:41], 0, v[130:131]
	s_mov_b32 m0, s55
	s_nop 0
	global_load_lds_dwordx4 v[222:223], off
	s_waitcnt vmcnt(8)
	s_waitcnt lgkmcnt(0)
	s_barrier
	s_setprio 1
	s_waitcnt lgkmcnt(0)
	v_mfma_f32_16x16x32_bf16 v[124:127], v[144:147], v[184:187], v[124:127]
	v_mfma_f32_16x16x32_bf16 v[120:123], v[152:155], v[184:187], v[120:123]
	v_mfma_f32_16x16x32_bf16 v[108:111], v[144:147], v[192:195], v[108:111]
	v_mfma_f32_16x16x32_bf16 v[104:107], v[152:155], v[192:195], v[104:107]
	v_mfma_f32_16x16x32_bf16 v[92:95], v[144:147], v[200:203], v[92:95]
	v_mfma_f32_16x16x32_bf16 v[88:91], v[152:155], v[200:203], v[88:91]
	v_mfma_f32_16x16x32_bf16 v[76:79], v[144:147], v[208:211], v[76:79]
	v_mfma_f32_16x16x32_bf16 v[72:75], v[152:155], v[208:211], v[72:75]
	v_mfma_f32_16x16x32_bf16 v[124:127], v[148:151], v[188:191], v[124:127]
	v_mfma_f32_16x16x32_bf16 v[120:123], v[156:159], v[188:191], v[120:123]
	v_mfma_f32_16x16x32_bf16 v[108:111], v[148:151], v[196:199], v[108:111]
	v_mfma_f32_16x16x32_bf16 v[104:107], v[156:159], v[196:199], v[104:107]
	v_mfma_f32_16x16x32_bf16 v[92:95], v[148:151], v[204:207], v[92:95]
	v_mfma_f32_16x16x32_bf16 v[88:91], v[156:159], v[204:207], v[88:91]
	v_mfma_f32_16x16x32_bf16 v[76:79], v[148:151], v[212:215], v[76:79]
	v_mfma_f32_16x16x32_bf16 v[72:75], v[156:159], v[212:215], v[72:75]
	s_setprio 0
	s_setprio 1
	v_mfma_f32_16x16x32_bf16 v[116:119], v[168:171], v[184:187], v[116:119]
	v_mfma_f32_16x16x32_bf16 v[112:115], v[176:179], v[184:187], v[112:115]
	v_mfma_f32_16x16x32_bf16 v[100:103], v[168:171], v[192:195], v[100:103]
	v_mfma_f32_16x16x32_bf16 v[96:99], v[176:179], v[192:195], v[96:99]
	v_mfma_f32_16x16x32_bf16 v[84:87], v[168:171], v[200:203], v[84:87]
	v_mfma_f32_16x16x32_bf16 v[80:83], v[176:179], v[200:203], v[80:83]
	v_mfma_f32_16x16x32_bf16 v[68:71], v[168:171], v[208:211], v[68:71]
	v_mfma_f32_16x16x32_bf16 v[64:67], v[176:179], v[208:211], v[64:67]
	s_setprio 2
	s_barrier
	v_mfma_f32_16x16x32_bf16 v[116:119], v[172:175], v[188:191], v[116:119]
	v_mfma_f32_16x16x32_bf16 v[112:115], v[180:183], v[188:191], v[112:115]
	v_mfma_f32_16x16x32_bf16 v[100:103], v[172:175], v[196:199], v[100:103]
	v_mfma_f32_16x16x32_bf16 v[96:99], v[180:183], v[196:199], v[96:99]
	v_mfma_f32_16x16x32_bf16 v[84:87], v[172:175], v[204:207], v[84:87]
	v_mfma_f32_16x16x32_bf16 v[80:83], v[180:183], v[204:207], v[80:83]
	v_mfma_f32_16x16x32_bf16 v[68:71], v[172:175], v[212:215], v[68:71]
	v_mfma_f32_16x16x32_bf16 v[64:67], v[180:183], v[212:215], v[64:67]
	s_setprio 0
	s_add_i32 s40, s66, s47
	v_lshl_add_u64 v[160:161], v[160:161], 0, s[16:17]
	s_mov_b32 m0, s40
	ds_read_b128 v[184:187], v165 offset:49152
	ds_read_b128 v[188:191], v165 offset:50176
	ds_read_b128 v[192:195], v165 offset:51200
	ds_read_b128 v[196:199], v165 offset:52224
	ds_read_b128 v[200:203], v165 offset:53248
	ds_read_b128 v[204:207], v165 offset:54272
	ds_read_b128 v[208:211], v165 offset:55296
	ds_read_b128 v[212:215], v165 offset:56320
	global_load_lds_dwordx4 v[160:161], off
	s_add_i32 m0, s40, 0x2000
	s_add_u32 s38, s38, 0x40080
	v_lshl_add_u64 v[160:161], v[216:217], 0, s[16:17]
	s_addc_u32 s39, s39, 0
	s_add_i32 s40, s67, s47
	global_load_lds_dwordx4 v[160:161], off
	v_lshl_add_u64 v[160:161], s[38:39], 0, v[132:133]
	s_mov_b32 m0, s40
	s_nop 0
	global_load_lds_dwordx4 v[160:161], off
	v_lshl_add_u64 v[160:161], s[38:39], 0, v[128:129]
	s_add_i32 m0, s40, 0x2000
	s_nop 0
	global_load_lds_dwordx4 v[160:161], off
	v_lshl_add_u64 v[160:161], v[218:219], 0, s[16:17]
	s_mov_b32 m0, s57
	s_nop 0
	global_load_lds_dwordx4 v[160:161], off
	v_lshl_add_u64 v[160:161], v[220:221], 0, s[16:17]
	s_mov_b32 m0, s58
	s_nop 0
	global_load_lds_dwordx4 v[160:161], off
	s_waitcnt vmcnt(8)
	s_waitcnt lgkmcnt(0)
	s_barrier
	s_setprio 1
	s_waitcnt lgkmcnt(0)
	v_mfma_f32_16x16x32_bf16 v[60:63], v[144:147], v[184:187], v[60:63]
	v_mfma_f32_16x16x32_bf16 v[56:59], v[152:155], v[184:187], v[56:59]
	v_mfma_f32_16x16x32_bf16 v[44:47], v[144:147], v[192:195], v[44:47]
	v_mfma_f32_16x16x32_bf16 v[40:43], v[152:155], v[192:195], v[40:43]
	v_mfma_f32_16x16x32_bf16 v[28:31], v[144:147], v[200:203], v[28:31]
	v_mfma_f32_16x16x32_bf16 v[24:27], v[152:155], v[200:203], v[24:27]
	v_mfma_f32_16x16x32_bf16 v[12:15], v[144:147], v[208:211], v[12:15]
	v_mfma_f32_16x16x32_bf16 v[8:11], v[152:155], v[208:211], v[8:11]
	v_mfma_f32_16x16x32_bf16 v[60:63], v[148:151], v[188:191], v[60:63]
	v_mfma_f32_16x16x32_bf16 v[56:59], v[156:159], v[188:191], v[56:59]
	v_mfma_f32_16x16x32_bf16 v[44:47], v[148:151], v[196:199], v[44:47]
	v_mfma_f32_16x16x32_bf16 v[40:43], v[156:159], v[196:199], v[40:43]
	v_mfma_f32_16x16x32_bf16 v[28:31], v[148:151], v[204:207], v[28:31]
	v_mfma_f32_16x16x32_bf16 v[24:27], v[156:159], v[204:207], v[24:27]
	v_mfma_f32_16x16x32_bf16 v[12:15], v[148:151], v[212:215], v[12:15]
	v_mfma_f32_16x16x32_bf16 v[8:11], v[156:159], v[212:215], v[8:11]
	s_setprio 0
	s_setprio 1
	v_mfma_f32_16x16x32_bf16 v[52:55], v[168:171], v[184:187], v[52:55]
	v_mfma_f32_16x16x32_bf16 v[48:51], v[176:179], v[184:187], v[48:51]
	v_mfma_f32_16x16x32_bf16 v[36:39], v[168:171], v[192:195], v[36:39]
	v_mfma_f32_16x16x32_bf16 v[32:35], v[176:179], v[192:195], v[32:35]
	v_mfma_f32_16x16x32_bf16 v[20:23], v[168:171], v[200:203], v[20:23]
	v_mfma_f32_16x16x32_bf16 v[16:19], v[176:179], v[200:203], v[16:19]
	v_mfma_f32_16x16x32_bf16 v[4:7], v[168:171], v[208:211], v[4:7]
	v_mfma_f32_16x16x32_bf16 v[0:3], v[176:179], v[208:211], v[0:3]
	s_setprio 2
	s_barrier
	v_mfma_f32_16x16x32_bf16 v[52:55], v[172:175], v[188:191], v[52:55]
	v_mfma_f32_16x16x32_bf16 v[48:51], v[180:183], v[188:191], v[48:51]
	v_mfma_f32_16x16x32_bf16 v[36:39], v[172:175], v[196:199], v[36:39]
	v_mfma_f32_16x16x32_bf16 v[32:35], v[180:183], v[196:199], v[32:35]
	v_mfma_f32_16x16x32_bf16 v[20:23], v[172:175], v[204:207], v[20:23]
	v_mfma_f32_16x16x32_bf16 v[16:19], v[180:183], v[204:207], v[16:19]
	v_mfma_f32_16x16x32_bf16 v[4:7], v[172:175], v[212:215], v[4:7]
	v_mfma_f32_16x16x32_bf16 v[0:3], v[180:183], v[212:215], v[0:3]
	s_setprio 0
	s_add_i32 s65, s65, 2
	s_add_u32 s36, s36, 0x100
	s_addc_u32 s37, s37, 0
	s_add_u32 s63, s63, 0x100
	s_addc_u32 s64, s64, 0
	s_cmp_gt_u32 s65, 13
	s_cbranch_scc0 .LBB0_784

.LBB0_866:
	ds_read_b128 v[120:123], v233
	ds_read_b128 v[124:127], v233 offset:1024
	ds_read_b128 v[136:139], v233 offset:2048
	ds_read_b128 v[140:143], v233 offset:3072
	ds_read_b128 v[144:147], v234
	ds_read_b128 v[148:151], v234 offset:1024
	ds_read_b128 v[152:155], v234 offset:2048
	ds_read_b128 v[156:159], v234 offset:3072
	s_add_u32 s28, s26, 0x100
	s_addc_u32 s29, s27, 0
	s_cmp_eq_u32 s64, 40
	s_cselect_b32 s37, s7, s29
	s_cselect_b32 s36, s6, s28
	s_cselect_b32 s31, s25, s63
	s_cselect_b32 s30, s24, s62
	v_lshl_add_u64 v[208:209], s[26:27], 0, v[192:193]
	s_add_i32 m0, s44, 0xc000
	ds_read_b128 v[160:163], v235
	ds_read_b128 v[164:167], v235 offset:1024
	ds_read_b128 v[168:171], v235 offset:2048
	ds_read_b128 v[172:175], v235 offset:3072
	ds_read_b128 v[176:179], v235 offset:4096
	ds_read_b128 v[180:183], v235 offset:5120
	ds_read_b128 v[200:203], v235 offset:6144
	ds_read_b128 v[204:207], v235 offset:7168
	global_load_lds_dwordx4 v[208:209], off
	v_lshl_add_u64 v[208:209], s[26:27], 0, v[194:195]
	s_add_i32 m0, s44, 0xe000
	s_nop 0
	global_load_lds_dwordx4 v[208:209], off
	s_waitcnt vmcnt(8)
	s_waitcnt lgkmcnt(0)
	s_barrier
	s_setprio 1
	s_waitcnt lgkmcnt(0)
	v_mfma_f32_16x16x32_bf16 v[132:135], v[120:123], v[160:163], v[132:135]
	v_mfma_f32_16x16x32_bf16 v[128:131], v[136:139], v[160:163], v[128:131]
	v_mfma_f32_16x16x32_bf16 v[108:111], v[120:123], v[168:171], v[108:111]
	v_mfma_f32_16x16x32_bf16 v[104:107], v[136:139], v[168:171], v[104:107]
	v_mfma_f32_16x16x32_bf16 v[92:95], v[120:123], v[176:179], v[92:95]
	v_mfma_f32_16x16x32_bf16 v[88:91], v[136:139], v[176:179], v[88:91]
	v_mfma_f32_16x16x32_bf16 v[76:79], v[120:123], v[200:203], v[76:79]
	v_mfma_f32_16x16x32_bf16 v[72:75], v[136:139], v[200:203], v[72:75]
	v_mfma_f32_16x16x32_bf16 v[132:135], v[124:127], v[164:167], v[132:135]
	v_mfma_f32_16x16x32_bf16 v[128:131], v[140:143], v[164:167], v[128:131]
	v_mfma_f32_16x16x32_bf16 v[108:111], v[124:127], v[172:175], v[108:111]
	v_mfma_f32_16x16x32_bf16 v[104:107], v[140:143], v[172:175], v[104:107]
	v_mfma_f32_16x16x32_bf16 v[92:95], v[124:127], v[180:183], v[92:95]
	v_mfma_f32_16x16x32_bf16 v[88:91], v[140:143], v[180:183], v[88:91]
	v_mfma_f32_16x16x32_bf16 v[76:79], v[124:127], v[204:207], v[76:79]
	v_mfma_f32_16x16x32_bf16 v[72:75], v[140:143], v[204:207], v[72:75]
	s_setprio 0
	s_setprio 1
	v_mfma_f32_16x16x32_bf16 v[116:119], v[144:147], v[160:163], v[116:119]
	v_mfma_f32_16x16x32_bf16 v[112:115], v[152:155], v[160:163], v[112:115]
	v_mfma_f32_16x16x32_bf16 v[100:103], v[144:147], v[168:171], v[100:103]
	v_mfma_f32_16x16x32_bf16 v[96:99], v[152:155], v[168:171], v[96:99]
	v_mfma_f32_16x16x32_bf16 v[84:87], v[144:147], v[176:179], v[84:87]
	v_mfma_f32_16x16x32_bf16 v[80:83], v[152:155], v[176:179], v[80:83]
	v_mfma_f32_16x16x32_bf16 v[68:71], v[144:147], v[200:203], v[68:71]
	v_mfma_f32_16x16x32_bf16 v[64:67], v[152:155], v[200:203], v[64:67]
	s_setprio 2
	s_barrier
	v_mfma_f32_16x16x32_bf16 v[116:119], v[148:151], v[164:167], v[116:119]
	v_mfma_f32_16x16x32_bf16 v[112:115], v[156:159], v[164:167], v[112:115]
	v_mfma_f32_16x16x32_bf16 v[100:103], v[148:151], v[172:175], v[100:103]
	v_mfma_f32_16x16x32_bf16 v[96:99], v[156:159], v[172:175], v[96:99]
	v_mfma_f32_16x16x32_bf16 v[84:87], v[148:151], v[180:183], v[84:87]
	v_mfma_f32_16x16x32_bf16 v[80:83], v[156:159], v[180:183], v[80:83]
	v_mfma_f32_16x16x32_bf16 v[68:71], v[148:151], v[204:207], v[68:71]
	v_mfma_f32_16x16x32_bf16 v[64:67], v[156:159], v[204:207], v[64:67]
	s_setprio 0
	s_add_i32 s26, s56, s43
	v_lshl_add_u64 v[208:209], s[30:31], 0, v[186:187]
	s_mov_b32 m0, s26
	ds_read_b128 v[160:163], v235 offset:16384
	ds_read_b128 v[164:167], v235 offset:17408
	ds_read_b128 v[168:171], v235 offset:18432
	ds_read_b128 v[172:175], v235 offset:19456
	ds_read_b128 v[176:179], v235 offset:20480
	ds_read_b128 v[180:183], v235 offset:21504
	ds_read_b128 v[200:203], v235 offset:22528
	ds_read_b128 v[204:207], v235 offset:23552
	global_load_lds_dwordx4 v[208:209], off
	s_add_i32 m0, s26, 0x2000
	s_add_u32 s26, s30, 0xb0000
	v_lshl_add_u64 v[210:211], s[30:31], 0, v[190:191]
	s_addc_u32 s27, s31, 0
	s_add_i32 s65, s57, s43
	global_load_lds_dwordx4 v[210:211], off
	v_lshl_add_u64 v[212:213], s[26:27], 0, v[186:187]
	s_mov_b32 m0, s65
	v_lshl_add_u64 v[214:215], s[36:37], 0, v[188:189]
	global_load_lds_dwordx4 v[212:213], off
	v_lshl_add_u64 v[212:213], s[26:27], 0, v[190:191]
	s_add_i32 m0, s65, 0x2000
	s_nop 0
	global_load_lds_dwordx4 v[212:213], off
	v_lshl_add_u64 v[212:213], s[36:37], 0, v[184:185]
	s_mov_b32 m0, s44
	s_nop 0
	global_load_lds_dwordx4 v[212:213], off
	s_mov_b32 m0, s45
	s_nop 0
	global_load_lds_dwordx4 v[214:215], off
	s_waitcnt vmcnt(8)
	s_waitcnt lgkmcnt(0)
	s_barrier
	s_setprio 1
	s_waitcnt lgkmcnt(0)
	v_mfma_f32_16x16x32_bf16 v[60:63], v[120:123], v[160:163], v[60:63]
	v_mfma_f32_16x16x32_bf16 v[56:59], v[136:139], v[160:163], v[56:59]
	v_mfma_f32_16x16x32_bf16 v[44:47], v[120:123], v[168:171], v[44:47]
	v_mfma_f32_16x16x32_bf16 v[40:43], v[136:139], v[168:171], v[40:43]
	v_mfma_f32_16x16x32_bf16 v[28:31], v[120:123], v[176:179], v[28:31]
	v_mfma_f32_16x16x32_bf16 v[24:27], v[136:139], v[176:179], v[24:27]
	v_mfma_f32_16x16x32_bf16 v[12:15], v[120:123], v[200:203], v[12:15]
	v_mfma_f32_16x16x32_bf16 v[8:11], v[136:139], v[200:203], v[8:11]
	v_mfma_f32_16x16x32_bf16 v[60:63], v[124:127], v[164:167], v[60:63]
	v_mfma_f32_16x16x32_bf16 v[56:59], v[140:143], v[164:167], v[56:59]
	v_mfma_f32_16x16x32_bf16 v[44:47], v[124:127], v[172:175], v[44:47]
	v_mfma_f32_16x16x32_bf16 v[40:43], v[140:143], v[172:175], v[40:43]
	v_mfma_f32_16x16x32_bf16 v[28:31], v[124:127], v[180:183], v[28:31]
	v_mfma_f32_16x16x32_bf16 v[24:27], v[140:143], v[180:183], v[24:27]
	v_mfma_f32_16x16x32_bf16 v[12:15], v[124:127], v[204:207], v[12:15]
	v_mfma_f32_16x16x32_bf16 v[8:11], v[140:143], v[204:207], v[8:11]
	s_setprio 0
	s_setprio 1
	v_mfma_f32_16x16x32_bf16 v[52:55], v[144:147], v[160:163], v[52:55]
	v_mfma_f32_16x16x32_bf16 v[48:51], v[152:155], v[160:163], v[48:51]
	v_mfma_f32_16x16x32_bf16 v[36:39], v[144:147], v[168:171], v[36:39]
	v_mfma_f32_16x16x32_bf16 v[32:35], v[152:155], v[168:171], v[32:35]
	v_mfma_f32_16x16x32_bf16 v[20:23], v[144:147], v[176:179], v[20:23]
	v_mfma_f32_16x16x32_bf16 v[16:19], v[152:155], v[176:179], v[16:19]
	v_mfma_f32_16x16x32_bf16 v[4:7], v[144:147], v[200:203], v[4:7]
	v_mfma_f32_16x16x32_bf16 v[0:3], v[152:155], v[200:203], v[0:3]
	s_setprio 2
	s_barrier
	v_mfma_f32_16x16x32_bf16 v[52:55], v[148:151], v[164:167], v[52:55]
	v_mfma_f32_16x16x32_bf16 v[48:51], v[156:159], v[164:167], v[48:51]
	v_mfma_f32_16x16x32_bf16 v[36:39], v[148:151], v[172:175], v[36:39]
	v_mfma_f32_16x16x32_bf16 v[32:35], v[156:159], v[172:175], v[32:35]
	v_mfma_f32_16x16x32_bf16 v[20:23], v[148:151], v[180:183], v[20:23]
	v_mfma_f32_16x16x32_bf16 v[16:19], v[156:159], v[180:183], v[16:19]
	v_mfma_f32_16x16x32_bf16 v[4:7], v[148:151], v[204:207], v[4:7]
	v_mfma_f32_16x16x32_bf16 v[0:3], v[156:159], v[204:207], v[0:3]
	s_setprio 0
	s_add_i32 s65, 0, 0x18000
	s_add_i32 s66, 0, 0x1c000
	v_add_u32_e32 v140, s65, v232
	v_add_u32_e32 v156, s66, v232
	ds_read_b128 v[120:123], v140
	ds_read_b128 v[124:127], v140 offset:1024
	ds_read_b128 v[136:139], v140 offset:2048
	ds_read_b128 v[140:143], v140 offset:3072
	ds_read_b128 v[144:147], v156
	ds_read_b128 v[148:151], v156 offset:1024
	ds_read_b128 v[152:155], v156 offset:2048
	ds_read_b128 v[156:159], v156 offset:3072
	s_add_u32 s26, s36, 0xb0000
	s_addc_u32 s27, s37, 0
	s_mov_b32 m0, s46
	v_lshl_add_u64 v[216:217], s[26:27], 0, v[184:185]
	ds_read_b128 v[160:163], v235 offset:32768
	ds_read_b128 v[164:167], v235 offset:33792
	ds_read_b128 v[168:171], v235 offset:34816
	ds_read_b128 v[172:175], v235 offset:35840
	ds_read_b128 v[176:179], v235 offset:36864
	ds_read_b128 v[180:183], v235 offset:37888
	ds_read_b128 v[200:203], v235 offset:38912
	ds_read_b128 v[204:207], v235 offset:39936
	global_load_lds_dwordx4 v[216:217], off
	v_lshl_add_u64 v[216:217], s[26:27], 0, v[188:189]
	s_mov_b32 m0, s47
	s_nop 0
	global_load_lds_dwordx4 v[216:217], off
	s_waitcnt vmcnt(8)
	s_waitcnt lgkmcnt(0)
	s_barrier
	s_setprio 1
	s_waitcnt lgkmcnt(0)
	v_mfma_f32_16x16x32_bf16 v[132:135], v[120:123], v[160:163], v[132:135]
	v_mfma_f32_16x16x32_bf16 v[128:131], v[136:139], v[160:163], v[128:131]
	v_mfma_f32_16x16x32_bf16 v[108:111], v[120:123], v[168:171], v[108:111]
	v_mfma_f32_16x16x32_bf16 v[104:107], v[136:139], v[168:171], v[104:107]
	v_mfma_f32_16x16x32_bf16 v[92:95], v[120:123], v[176:179], v[92:95]
	v_mfma_f32_16x16x32_bf16 v[88:91], v[136:139], v[176:179], v[88:91]
	v_mfma_f32_16x16x32_bf16 v[76:79], v[120:123], v[200:203], v[76:79]
	v_mfma_f32_16x16x32_bf16 v[72:75], v[136:139], v[200:203], v[72:75]
	v_mfma_f32_16x16x32_bf16 v[132:135], v[124:127], v[164:167], v[132:135]
	v_mfma_f32_16x16x32_bf16 v[128:131], v[140:143], v[164:167], v[128:131]
	v_mfma_f32_16x16x32_bf16 v[108:111], v[124:127], v[172:175], v[108:111]
	v_mfma_f32_16x16x32_bf16 v[104:107], v[140:143], v[172:175], v[104:107]
	v_mfma_f32_16x16x32_bf16 v[92:95], v[124:127], v[180:183], v[92:95]
	v_mfma_f32_16x16x32_bf16 v[88:91], v[140:143], v[180:183], v[88:91]
	v_mfma_f32_16x16x32_bf16 v[76:79], v[124:127], v[204:207], v[76:79]
	v_mfma_f32_16x16x32_bf16 v[72:75], v[140:143], v[204:207], v[72:75]
	s_setprio 0
	s_setprio 1
	v_mfma_f32_16x16x32_bf16 v[116:119], v[144:147], v[160:163], v[116:119]
	v_mfma_f32_16x16x32_bf16 v[112:115], v[152:155], v[160:163], v[112:115]
	v_mfma_f32_16x16x32_bf16 v[100:103], v[144:147], v[168:171], v[100:103]
	v_mfma_f32_16x16x32_bf16 v[96:99], v[152:155], v[168:171], v[96:99]
	v_mfma_f32_16x16x32_bf16 v[84:87], v[144:147], v[176:179], v[84:87]
	v_mfma_f32_16x16x32_bf16 v[80:83], v[152:155], v[176:179], v[80:83]
	v_mfma_f32_16x16x32_bf16 v[68:71], v[144:147], v[200:203], v[68:71]
	v_mfma_f32_16x16x32_bf16 v[64:67], v[152:155], v[200:203], v[64:67]
	s_setprio 2
	s_barrier
	v_mfma_f32_16x16x32_bf16 v[116:119], v[148:151], v[164:167], v[116:119]
	v_mfma_f32_16x16x32_bf16 v[112:115], v[156:159], v[164:167], v[112:115]
	v_mfma_f32_16x16x32_bf16 v[100:103], v[148:151], v[172:175], v[100:103]
	v_mfma_f32_16x16x32_bf16 v[96:99], v[156:159], v[172:175], v[96:99]
	v_mfma_f32_16x16x32_bf16 v[84:87], v[148:151], v[180:183], v[84:87]
	v_mfma_f32_16x16x32_bf16 v[80:83], v[156:159], v[180:183], v[80:83]
	v_mfma_f32_16x16x32_bf16 v[68:71], v[148:151], v[204:207], v[68:71]
	v_mfma_f32_16x16x32_bf16 v[64:67], v[156:159], v[204:207], v[64:67]
	s_setprio 0
	s_add_i32 s26, s65, s43
	v_lshl_add_u64 v[208:209], v[208:209], 0, s[20:21]
	s_mov_b32 m0, s26
	ds_read_b128 v[160:163], v235 offset:49152
	ds_read_b128 v[164:167], v235 offset:50176
	ds_read_b128 v[168:171], v235 offset:51200
	ds_read_b128 v[172:175], v235 offset:52224
	ds_read_b128 v[176:179], v235 offset:53248
	ds_read_b128 v[180:183], v235 offset:54272
	ds_read_b128 v[200:203], v235 offset:55296
	ds_read_b128 v[204:207], v235 offset:56320
	global_load_lds_dwordx4 v[208:209], off
	s_add_i32 m0, s26, 0x2000
	s_add_u32 s26, s30, 0xb0080
	v_lshl_add_u64 v[208:209], v[210:211], 0, s[20:21]
	s_addc_u32 s27, s31, 0
	s_add_i32 s30, s66, s43
	global_load_lds_dwordx4 v[208:209], off
	v_lshl_add_u64 v[208:209], s[26:27], 0, v[186:187]
	s_mov_b32 m0, s30
	s_nop 0
	global_load_lds_dwordx4 v[208:209], off
	v_lshl_add_u64 v[208:209], s[26:27], 0, v[190:191]
	s_add_i32 m0, s30, 0x2000
	s_nop 0
	global_load_lds_dwordx4 v[208:209], off
	v_lshl_add_u64 v[208:209], v[212:213], 0, s[20:21]
	s_mov_b32 m0, s49
	s_nop 0
	global_load_lds_dwordx4 v[208:209], off
	v_lshl_add_u64 v[208:209], v[214:215], 0, s[20:21]
	s_mov_b32 m0, s50
	s_nop 0
	global_load_lds_dwordx4 v[208:209], off
	s_waitcnt vmcnt(8)
	s_waitcnt lgkmcnt(0)
	s_barrier
	s_setprio 1
	s_waitcnt lgkmcnt(0)
	v_mfma_f32_16x16x32_bf16 v[60:63], v[120:123], v[160:163], v[60:63]
	v_mfma_f32_16x16x32_bf16 v[56:59], v[136:139], v[160:163], v[56:59]
	v_mfma_f32_16x16x32_bf16 v[44:47], v[120:123], v[168:171], v[44:47]
	v_mfma_f32_16x16x32_bf16 v[40:43], v[136:139], v[168:171], v[40:43]
	v_mfma_f32_16x16x32_bf16 v[28:31], v[120:123], v[176:179], v[28:31]
	v_mfma_f32_16x16x32_bf16 v[24:27], v[136:139], v[176:179], v[24:27]
	v_mfma_f32_16x16x32_bf16 v[12:15], v[120:123], v[200:203], v[12:15]
	v_mfma_f32_16x16x32_bf16 v[8:11], v[136:139], v[200:203], v[8:11]
	v_mfma_f32_16x16x32_bf16 v[60:63], v[124:127], v[164:167], v[60:63]
	v_mfma_f32_16x16x32_bf16 v[56:59], v[140:143], v[164:167], v[56:59]
	v_mfma_f32_16x16x32_bf16 v[44:47], v[124:127], v[172:175], v[44:47]
	v_mfma_f32_16x16x32_bf16 v[40:43], v[140:143], v[172:175], v[40:43]
	v_mfma_f32_16x16x32_bf16 v[28:31], v[124:127], v[180:183], v[28:31]
	v_mfma_f32_16x16x32_bf16 v[24:27], v[140:143], v[180:183], v[24:27]
	v_mfma_f32_16x16x32_bf16 v[12:15], v[124:127], v[204:207], v[12:15]
	v_mfma_f32_16x16x32_bf16 v[8:11], v[140:143], v[204:207], v[8:11]
	s_setprio 0
	s_setprio 1
	v_mfma_f32_16x16x32_bf16 v[52:55], v[144:147], v[160:163], v[52:55]
	v_mfma_f32_16x16x32_bf16 v[48:51], v[152:155], v[160:163], v[48:51]
	v_mfma_f32_16x16x32_bf16 v[36:39], v[144:147], v[168:171], v[36:39]
	v_mfma_f32_16x16x32_bf16 v[32:35], v[152:155], v[168:171], v[32:35]
	v_mfma_f32_16x16x32_bf16 v[20:23], v[144:147], v[176:179], v[20:23]
	v_mfma_f32_16x16x32_bf16 v[16:19], v[152:155], v[176:179], v[16:19]
	v_mfma_f32_16x16x32_bf16 v[4:7], v[144:147], v[200:203], v[4:7]
	v_mfma_f32_16x16x32_bf16 v[0:3], v[152:155], v[200:203], v[0:3]
	s_setprio 2
	s_barrier
	v_mfma_f32_16x16x32_bf16 v[52:55], v[148:151], v[164:167], v[52:55]
	v_mfma_f32_16x16x32_bf16 v[48:51], v[156:159], v[164:167], v[48:51]
	v_mfma_f32_16x16x32_bf16 v[36:39], v[148:151], v[172:175], v[36:39]
	v_mfma_f32_16x16x32_bf16 v[32:35], v[156:159], v[172:175], v[32:35]
	v_mfma_f32_16x16x32_bf16 v[20:23], v[148:151], v[180:183], v[20:23]
	v_mfma_f32_16x16x32_bf16 v[16:19], v[156:159], v[180:183], v[16:19]
	v_mfma_f32_16x16x32_bf16 v[4:7], v[148:151], v[204:207], v[4:7]
	v_mfma_f32_16x16x32_bf16 v[0:3], v[156:159], v[204:207], v[0:3]
	s_setprio 0
	s_add_i32 s64, s64, 2
	s_add_u32 s62, s62, 0x100
	s_addc_u32 s63, s63, 0
	s_cmp_gt_u32 s64, 41
	s_mov_b64 s[26:27], s[28:29]
	s_cbranch_scc0 .LBB0_866

.LBB0_952:
	ds_read_b128 v[144:147], v179
	ds_read_b128 v[148:151], v179 offset:1024
	ds_read_b128 v[152:155], v179 offset:2048
	ds_read_b128 v[156:159], v179 offset:3072
	ds_read_b128 v[160:163], v180
	ds_read_b128 v[164:167], v180 offset:1024
	ds_read_b128 v[168:171], v180 offset:2048
	ds_read_b128 v[172:175], v180 offset:3072
	s_add_u32 s40, s6, 0xfffc0080
	s_addc_u32 s41, s7, -1
	s_cmp_eq_u32 s73, 12
	s_cselect_b32 s45, s27, s41
	s_cselect_b32 s44, s39, s40
	s_cselect_b32 s41, s29, s72
	s_cselect_b32 s40, s43, s71
	v_lshl_add_u64 v[176:177], s[6:7], 0, v[136:137]
	s_add_i32 m0, s54, 0xc000
	ds_read_b128 v[184:187], v181
	ds_read_b128 v[188:191], v181 offset:1024
	ds_read_b128 v[192:195], v181 offset:2048
	ds_read_b128 v[196:199], v181 offset:3072
	ds_read_b128 v[200:203], v181 offset:4096
	ds_read_b128 v[204:207], v181 offset:5120
	ds_read_b128 v[208:211], v181 offset:6144
	ds_read_b128 v[212:215], v181 offset:7168
	global_load_lds_dwordx4 v[176:177], off
	v_lshl_add_u64 v[176:177], s[6:7], 0, v[138:139]
	s_add_i32 m0, s54, 0xe000
	s_nop 0
	global_load_lds_dwordx4 v[176:177], off
	s_waitcnt vmcnt(8)
	s_waitcnt lgkmcnt(0)
	s_barrier
	s_setprio 1
	s_waitcnt lgkmcnt(0)
	v_mfma_f32_16x16x32_bf16 v[124:127], v[144:147], v[184:187], v[124:127]
	v_mfma_f32_16x16x32_bf16 v[120:123], v[152:155], v[184:187], v[120:123]
	v_mfma_f32_16x16x32_bf16 v[108:111], v[144:147], v[192:195], v[108:111]
	v_mfma_f32_16x16x32_bf16 v[104:107], v[152:155], v[192:195], v[104:107]
	v_mfma_f32_16x16x32_bf16 v[92:95], v[144:147], v[200:203], v[92:95]
	v_mfma_f32_16x16x32_bf16 v[88:91], v[152:155], v[200:203], v[88:91]
	v_mfma_f32_16x16x32_bf16 v[76:79], v[144:147], v[208:211], v[76:79]
	v_mfma_f32_16x16x32_bf16 v[72:75], v[152:155], v[208:211], v[72:75]
	v_mfma_f32_16x16x32_bf16 v[124:127], v[148:151], v[188:191], v[124:127]
	v_mfma_f32_16x16x32_bf16 v[120:123], v[156:159], v[188:191], v[120:123]
	v_mfma_f32_16x16x32_bf16 v[108:111], v[148:151], v[196:199], v[108:111]
	v_mfma_f32_16x16x32_bf16 v[104:107], v[156:159], v[196:199], v[104:107]
	v_mfma_f32_16x16x32_bf16 v[92:95], v[148:151], v[204:207], v[92:95]
	v_mfma_f32_16x16x32_bf16 v[88:91], v[156:159], v[204:207], v[88:91]
	v_mfma_f32_16x16x32_bf16 v[76:79], v[148:151], v[212:215], v[76:79]
	v_mfma_f32_16x16x32_bf16 v[72:75], v[156:159], v[212:215], v[72:75]
	s_setprio 0
	s_setprio 1
	v_mfma_f32_16x16x32_bf16 v[116:119], v[160:163], v[184:187], v[116:119]
	v_mfma_f32_16x16x32_bf16 v[112:115], v[168:171], v[184:187], v[112:115]
	v_mfma_f32_16x16x32_bf16 v[100:103], v[160:163], v[192:195], v[100:103]
	v_mfma_f32_16x16x32_bf16 v[96:99], v[168:171], v[192:195], v[96:99]
	v_mfma_f32_16x16x32_bf16 v[84:87], v[160:163], v[200:203], v[84:87]
	v_mfma_f32_16x16x32_bf16 v[80:83], v[168:171], v[200:203], v[80:83]
	v_mfma_f32_16x16x32_bf16 v[68:71], v[160:163], v[208:211], v[68:71]
	v_mfma_f32_16x16x32_bf16 v[64:67], v[168:171], v[208:211], v[64:67]
	s_setprio 2
	s_barrier
	v_mfma_f32_16x16x32_bf16 v[116:119], v[164:167], v[188:191], v[116:119]
	v_mfma_f32_16x16x32_bf16 v[112:115], v[172:175], v[188:191], v[112:115]
	v_mfma_f32_16x16x32_bf16 v[100:103], v[164:167], v[196:199], v[100:103]
	v_mfma_f32_16x16x32_bf16 v[96:99], v[172:175], v[196:199], v[96:99]
	v_mfma_f32_16x16x32_bf16 v[84:87], v[164:167], v[204:207], v[84:87]
	v_mfma_f32_16x16x32_bf16 v[80:83], v[172:175], v[204:207], v[80:83]
	v_mfma_f32_16x16x32_bf16 v[68:71], v[164:167], v[212:215], v[68:71]
	v_mfma_f32_16x16x32_bf16 v[64:67], v[172:175], v[212:215], v[64:67]
	s_setprio 0
	s_add_i32 s74, s69, s51
	v_lshl_add_u64 v[176:177], s[40:41], 0, v[130:131]
	s_mov_b32 m0, s74
	ds_read_b128 v[184:187], v181 offset:16384
	ds_read_b128 v[188:191], v181 offset:17408
	ds_read_b128 v[192:195], v181 offset:18432
	ds_read_b128 v[196:199], v181 offset:19456
	ds_read_b128 v[200:203], v181 offset:20480
	ds_read_b128 v[204:207], v181 offset:21504
	ds_read_b128 v[208:211], v181 offset:22528
	ds_read_b128 v[212:215], v181 offset:23552
	global_load_lds_dwordx4 v[176:177], off
	s_add_i32 m0, s74, 0x2000
	s_add_u32 s74, s40, 0x40000
	v_lshl_add_u64 v[216:217], s[40:41], 0, v[134:135]
	s_addc_u32 s75, s41, 0
	s_add_i32 s76, s70, s51
	global_load_lds_dwordx4 v[216:217], off
	v_lshl_add_u64 v[218:219], s[74:75], 0, v[130:131]
	s_mov_b32 m0, s76
	v_lshl_add_u64 v[220:221], s[44:45], 0, v[132:133]
	global_load_lds_dwordx4 v[218:219], off
	v_lshl_add_u64 v[218:219], s[74:75], 0, v[134:135]
	s_add_i32 m0, s76, 0x2000
	s_nop 0
	global_load_lds_dwordx4 v[218:219], off
	v_lshl_add_u64 v[218:219], s[44:45], 0, v[128:129]
	s_mov_b32 m0, s54
	s_nop 0
	global_load_lds_dwordx4 v[218:219], off
	s_mov_b32 m0, s55
	s_nop 0
	global_load_lds_dwordx4 v[220:221], off
	s_waitcnt vmcnt(8)
	s_waitcnt lgkmcnt(0)
	s_barrier
	s_setprio 1
	s_waitcnt lgkmcnt(0)
	v_mfma_f32_16x16x32_bf16 v[60:63], v[144:147], v[184:187], v[60:63]
	v_mfma_f32_16x16x32_bf16 v[56:59], v[152:155], v[184:187], v[56:59]
	v_mfma_f32_16x16x32_bf16 v[44:47], v[144:147], v[192:195], v[44:47]
	v_mfma_f32_16x16x32_bf16 v[40:43], v[152:155], v[192:195], v[40:43]
	v_mfma_f32_16x16x32_bf16 v[28:31], v[144:147], v[200:203], v[28:31]
	v_mfma_f32_16x16x32_bf16 v[24:27], v[152:155], v[200:203], v[24:27]
	v_mfma_f32_16x16x32_bf16 v[12:15], v[144:147], v[208:211], v[12:15]
	v_mfma_f32_16x16x32_bf16 v[8:11], v[152:155], v[208:211], v[8:11]
	v_mfma_f32_16x16x32_bf16 v[60:63], v[148:151], v[188:191], v[60:63]
	v_mfma_f32_16x16x32_bf16 v[56:59], v[156:159], v[188:191], v[56:59]
	v_mfma_f32_16x16x32_bf16 v[44:47], v[148:151], v[196:199], v[44:47]
	v_mfma_f32_16x16x32_bf16 v[40:43], v[156:159], v[196:199], v[40:43]
	v_mfma_f32_16x16x32_bf16 v[28:31], v[148:151], v[204:207], v[28:31]
	v_mfma_f32_16x16x32_bf16 v[24:27], v[156:159], v[204:207], v[24:27]
	v_mfma_f32_16x16x32_bf16 v[12:15], v[148:151], v[212:215], v[12:15]
	v_mfma_f32_16x16x32_bf16 v[8:11], v[156:159], v[212:215], v[8:11]
	s_setprio 0
	s_setprio 1
	v_mfma_f32_16x16x32_bf16 v[52:55], v[160:163], v[184:187], v[52:55]
	v_mfma_f32_16x16x32_bf16 v[48:51], v[168:171], v[184:187], v[48:51]
	v_mfma_f32_16x16x32_bf16 v[36:39], v[160:163], v[192:195], v[36:39]
	v_mfma_f32_16x16x32_bf16 v[32:35], v[168:171], v[192:195], v[32:35]
	v_mfma_f32_16x16x32_bf16 v[20:23], v[160:163], v[200:203], v[20:23]
	v_mfma_f32_16x16x32_bf16 v[16:19], v[168:171], v[200:203], v[16:19]
	v_mfma_f32_16x16x32_bf16 v[4:7], v[160:163], v[208:211], v[4:7]
	v_mfma_f32_16x16x32_bf16 v[0:3], v[168:171], v[208:211], v[0:3]
	s_setprio 2
	s_barrier
	v_mfma_f32_16x16x32_bf16 v[52:55], v[164:167], v[188:191], v[52:55]
	v_mfma_f32_16x16x32_bf16 v[48:51], v[172:175], v[188:191], v[48:51]
	v_mfma_f32_16x16x32_bf16 v[36:39], v[164:167], v[196:199], v[36:39]
	v_mfma_f32_16x16x32_bf16 v[32:35], v[172:175], v[196:199], v[32:35]
	v_mfma_f32_16x16x32_bf16 v[20:23], v[164:167], v[204:207], v[20:23]
	v_mfma_f32_16x16x32_bf16 v[16:19], v[172:175], v[204:207], v[16:19]
	v_mfma_f32_16x16x32_bf16 v[4:7], v[164:167], v[212:215], v[4:7]
	v_mfma_f32_16x16x32_bf16 v[0:3], v[172:175], v[212:215], v[0:3]
	s_setprio 0
	s_add_i32 s74, 0, 0x18000
	s_add_i32 s75, 0, 0x1c000
	v_add_u32_e32 v156, s74, v178
	v_add_u32_e32 v172, s75, v178
	ds_read_b128 v[144:147], v156
	ds_read_b128 v[148:151], v156 offset:1024
	ds_read_b128 v[152:155], v156 offset:2048
	ds_read_b128 v[156:159], v156 offset:3072
	ds_read_b128 v[160:163], v172
	ds_read_b128 v[164:167], v172 offset:1024
	ds_read_b128 v[168:171], v172 offset:2048
	ds_read_b128 v[172:175], v172 offset:3072
	s_add_u32 s44, s44, 0x40000
	s_addc_u32 s45, s45, 0
	s_mov_b32 m0, s56
	v_lshl_add_u64 v[222:223], s[44:45], 0, v[128:129]
	ds_read_b128 v[184:187], v181 offset:32768
	ds_read_b128 v[188:191], v181 offset:33792
	ds_read_b128 v[192:195], v181 offset:34816
	ds_read_b128 v[196:199], v181 offset:35840
	ds_read_b128 v[200:203], v181 offset:36864
	ds_read_b128 v[204:207], v181 offset:37888
	ds_read_b128 v[208:211], v181 offset:38912
	ds_read_b128 v[212:215], v181 offset:39936
	global_load_lds_dwordx4 v[222:223], off
	v_lshl_add_u64 v[222:223], s[44:45], 0, v[132:133]
	s_mov_b32 m0, s57
	s_nop 0
	global_load_lds_dwordx4 v[222:223], off
	s_waitcnt vmcnt(8)
	s_waitcnt lgkmcnt(0)
	s_barrier
	s_setprio 1
	s_waitcnt lgkmcnt(0)
	v_mfma_f32_16x16x32_bf16 v[124:127], v[144:147], v[184:187], v[124:127]
	v_mfma_f32_16x16x32_bf16 v[120:123], v[152:155], v[184:187], v[120:123]
	v_mfma_f32_16x16x32_bf16 v[108:111], v[144:147], v[192:195], v[108:111]
	v_mfma_f32_16x16x32_bf16 v[104:107], v[152:155], v[192:195], v[104:107]
	v_mfma_f32_16x16x32_bf16 v[92:95], v[144:147], v[200:203], v[92:95]
	v_mfma_f32_16x16x32_bf16 v[88:91], v[152:155], v[200:203], v[88:91]
	v_mfma_f32_16x16x32_bf16 v[76:79], v[144:147], v[208:211], v[76:79]
	v_mfma_f32_16x16x32_bf16 v[72:75], v[152:155], v[208:211], v[72:75]
	v_mfma_f32_16x16x32_bf16 v[124:127], v[148:151], v[188:191], v[124:127]
	v_mfma_f32_16x16x32_bf16 v[120:123], v[156:159], v[188:191], v[120:123]
	v_mfma_f32_16x16x32_bf16 v[108:111], v[148:151], v[196:199], v[108:111]
	v_mfma_f32_16x16x32_bf16 v[104:107], v[156:159], v[196:199], v[104:107]
	v_mfma_f32_16x16x32_bf16 v[92:95], v[148:151], v[204:207], v[92:95]
	v_mfma_f32_16x16x32_bf16 v[88:91], v[156:159], v[204:207], v[88:91]
	v_mfma_f32_16x16x32_bf16 v[76:79], v[148:151], v[212:215], v[76:79]
	v_mfma_f32_16x16x32_bf16 v[72:75], v[156:159], v[212:215], v[72:75]
	s_setprio 0
	s_setprio 1
	v_mfma_f32_16x16x32_bf16 v[116:119], v[160:163], v[184:187], v[116:119]
	v_mfma_f32_16x16x32_bf16 v[112:115], v[168:171], v[184:187], v[112:115]
	v_mfma_f32_16x16x32_bf16 v[100:103], v[160:163], v[192:195], v[100:103]
	v_mfma_f32_16x16x32_bf16 v[96:99], v[168:171], v[192:195], v[96:99]
	v_mfma_f32_16x16x32_bf16 v[84:87], v[160:163], v[200:203], v[84:87]
	v_mfma_f32_16x16x32_bf16 v[80:83], v[168:171], v[200:203], v[80:83]
	v_mfma_f32_16x16x32_bf16 v[68:71], v[160:163], v[208:211], v[68:71]
	v_mfma_f32_16x16x32_bf16 v[64:67], v[168:171], v[208:211], v[64:67]
	s_setprio 2
	s_barrier
	v_mfma_f32_16x16x32_bf16 v[116:119], v[164:167], v[188:191], v[116:119]
	v_mfma_f32_16x16x32_bf16 v[112:115], v[172:175], v[188:191], v[112:115]
	v_mfma_f32_16x16x32_bf16 v[100:103], v[164:167], v[196:199], v[100:103]
	v_mfma_f32_16x16x32_bf16 v[96:99], v[172:175], v[196:199], v[96:99]
	v_mfma_f32_16x16x32_bf16 v[84:87], v[164:167], v[204:207], v[84:87]
	v_mfma_f32_16x16x32_bf16 v[80:83], v[172:175], v[204:207], v[80:83]
	v_mfma_f32_16x16x32_bf16 v[68:71], v[164:167], v[212:215], v[68:71]
	v_mfma_f32_16x16x32_bf16 v[64:67], v[172:175], v[212:215], v[64:67]
	s_setprio 0
	s_add_i32 s44, s74, s51
	v_lshl_add_u64 v[176:177], v[176:177], 0, s[22:23]
	s_mov_b32 m0, s44
	ds_read_b128 v[184:187], v181 offset:49152
	ds_read_b128 v[188:191], v181 offset:50176
	ds_read_b128 v[192:195], v181 offset:51200
	ds_read_b128 v[196:199], v181 offset:52224
	ds_read_b128 v[200:203], v181 offset:53248
	ds_read_b128 v[204:207], v181 offset:54272
	ds_read_b128 v[208:211], v181 offset:55296
	ds_read_b128 v[212:215], v181 offset:56320
	global_load_lds_dwordx4 v[176:177], off
	s_add_i32 m0, s44, 0x2000
	s_add_u32 s40, s40, 0x40080
	v_lshl_add_u64 v[176:177], v[216:217], 0, s[22:23]
	s_addc_u32 s41, s41, 0
	s_add_i32 s44, s75, s51
	global_load_lds_dwordx4 v[176:177], off
	v_lshl_add_u64 v[176:177], s[40:41], 0, v[130:131]
	s_mov_b32 m0, s44
	s_nop 0
	global_load_lds_dwordx4 v[176:177], off
	v_lshl_add_u64 v[176:177], s[40:41], 0, v[134:135]
	s_add_i32 m0, s44, 0x2000
	s_nop 0
	global_load_lds_dwordx4 v[176:177], off
	v_lshl_add_u64 v[176:177], v[218:219], 0, s[22:23]
	s_mov_b32 m0, s64
	s_nop 0
	global_load_lds_dwordx4 v[176:177], off
	v_lshl_add_u64 v[176:177], v[220:221], 0, s[22:23]
	s_mov_b32 m0, s65
	s_nop 0
	global_load_lds_dwordx4 v[176:177], off
	s_waitcnt vmcnt(8)
	s_waitcnt lgkmcnt(0)
	s_barrier
	s_setprio 1
	s_waitcnt lgkmcnt(0)
	v_mfma_f32_16x16x32_bf16 v[60:63], v[144:147], v[184:187], v[60:63]
	v_mfma_f32_16x16x32_bf16 v[56:59], v[152:155], v[184:187], v[56:59]
	v_mfma_f32_16x16x32_bf16 v[44:47], v[144:147], v[192:195], v[44:47]
	v_mfma_f32_16x16x32_bf16 v[40:43], v[152:155], v[192:195], v[40:43]
	v_mfma_f32_16x16x32_bf16 v[28:31], v[144:147], v[200:203], v[28:31]
	v_mfma_f32_16x16x32_bf16 v[24:27], v[152:155], v[200:203], v[24:27]
	v_mfma_f32_16x16x32_bf16 v[12:15], v[144:147], v[208:211], v[12:15]
	v_mfma_f32_16x16x32_bf16 v[8:11], v[152:155], v[208:211], v[8:11]
	v_mfma_f32_16x16x32_bf16 v[60:63], v[148:151], v[188:191], v[60:63]
	v_mfma_f32_16x16x32_bf16 v[56:59], v[156:159], v[188:191], v[56:59]
	v_mfma_f32_16x16x32_bf16 v[44:47], v[148:151], v[196:199], v[44:47]
	v_mfma_f32_16x16x32_bf16 v[40:43], v[156:159], v[196:199], v[40:43]
	v_mfma_f32_16x16x32_bf16 v[28:31], v[148:151], v[204:207], v[28:31]
	v_mfma_f32_16x16x32_bf16 v[24:27], v[156:159], v[204:207], v[24:27]
	v_mfma_f32_16x16x32_bf16 v[12:15], v[148:151], v[212:215], v[12:15]
	v_mfma_f32_16x16x32_bf16 v[8:11], v[156:159], v[212:215], v[8:11]
	s_setprio 0
	s_setprio 1
	v_mfma_f32_16x16x32_bf16 v[52:55], v[160:163], v[184:187], v[52:55]
	v_mfma_f32_16x16x32_bf16 v[48:51], v[168:171], v[184:187], v[48:51]
	v_mfma_f32_16x16x32_bf16 v[36:39], v[160:163], v[192:195], v[36:39]
	v_mfma_f32_16x16x32_bf16 v[32:35], v[168:171], v[192:195], v[32:35]
	v_mfma_f32_16x16x32_bf16 v[20:23], v[160:163], v[200:203], v[20:23]
	v_mfma_f32_16x16x32_bf16 v[16:19], v[168:171], v[200:203], v[16:19]
	v_mfma_f32_16x16x32_bf16 v[4:7], v[160:163], v[208:211], v[4:7]
	v_mfma_f32_16x16x32_bf16 v[0:3], v[168:171], v[208:211], v[0:3]
	s_setprio 2
	s_barrier
	v_mfma_f32_16x16x32_bf16 v[52:55], v[164:167], v[188:191], v[52:55]
	v_mfma_f32_16x16x32_bf16 v[48:51], v[172:175], v[188:191], v[48:51]
	v_mfma_f32_16x16x32_bf16 v[36:39], v[164:167], v[196:199], v[36:39]
	v_mfma_f32_16x16x32_bf16 v[32:35], v[172:175], v[196:199], v[32:35]
	v_mfma_f32_16x16x32_bf16 v[20:23], v[164:167], v[204:207], v[20:23]
	v_mfma_f32_16x16x32_bf16 v[16:19], v[172:175], v[204:207], v[16:19]
	v_mfma_f32_16x16x32_bf16 v[4:7], v[164:167], v[212:215], v[4:7]
	v_mfma_f32_16x16x32_bf16 v[0:3], v[172:175], v[212:215], v[0:3]
	s_setprio 0
	s_add_i32 s73, s73, 2
	s_add_u32 s6, s6, 0x100
	s_addc_u32 s7, s7, 0
	s_add_u32 s71, s71, 0x100
	s_addc_u32 s72, s72, 0
	s_cmp_gt_u32 s73, 13
	s_cbranch_scc0 .LBB0_952

.LBB0_1146:
	ds_read_b128 v[120:123], v233
	ds_read_b128 v[132:135], v233 offset:1024
	ds_read_b128 v[136:139], v233 offset:2048
	ds_read_b128 v[140:143], v233 offset:3072
	ds_read_b128 v[144:147], v234
	ds_read_b128 v[148:151], v234 offset:1024
	ds_read_b128 v[152:155], v234 offset:2048
	ds_read_b128 v[156:159], v234 offset:3072
	s_add_u32 s40, s38, 0xfffc0080
	s_addc_u32 s41, s39, -1
	s_cmp_eq_u32 s66, 12
	s_cselect_b32 s43, s23, s41
	s_cselect_b32 s42, s31, s40
	s_cselect_b32 s41, s25, s65
	s_cselect_b32 s40, s37, s64
	v_lshl_add_u64 v[208:209], s[38:39], 0, v[192:193]
	s_add_i32 m0, s50, 0xc000
	ds_read_b128 v[160:163], v235
	ds_read_b128 v[164:167], v235 offset:1024
	ds_read_b128 v[168:171], v235 offset:2048
	ds_read_b128 v[172:175], v235 offset:3072
	ds_read_b128 v[176:179], v235 offset:4096
	ds_read_b128 v[180:183], v235 offset:5120
	ds_read_b128 v[200:203], v235 offset:6144
	ds_read_b128 v[204:207], v235 offset:7168
	global_load_lds_dwordx4 v[208:209], off
	v_lshl_add_u64 v[208:209], s[38:39], 0, v[194:195]
	s_add_i32 m0, s50, 0xe000
	s_nop 0
	global_load_lds_dwordx4 v[208:209], off
	s_waitcnt vmcnt(8)
	s_waitcnt lgkmcnt(0)
	s_barrier
	s_setprio 1
	s_waitcnt lgkmcnt(0)
	v_mfma_f32_16x16x32_bf16 v[128:131], v[120:123], v[160:163], v[128:131]
	v_mfma_f32_16x16x32_bf16 v[124:127], v[136:139], v[160:163], v[124:127]
	v_mfma_f32_16x16x32_bf16 v[108:111], v[120:123], v[168:171], v[108:111]
	v_mfma_f32_16x16x32_bf16 v[104:107], v[136:139], v[168:171], v[104:107]
	v_mfma_f32_16x16x32_bf16 v[92:95], v[120:123], v[176:179], v[92:95]
	v_mfma_f32_16x16x32_bf16 v[88:91], v[136:139], v[176:179], v[88:91]
	v_mfma_f32_16x16x32_bf16 v[76:79], v[120:123], v[200:203], v[76:79]
	v_mfma_f32_16x16x32_bf16 v[72:75], v[136:139], v[200:203], v[72:75]
	v_mfma_f32_16x16x32_bf16 v[128:131], v[132:135], v[164:167], v[128:131]
	v_mfma_f32_16x16x32_bf16 v[124:127], v[140:143], v[164:167], v[124:127]
	v_mfma_f32_16x16x32_bf16 v[108:111], v[132:135], v[172:175], v[108:111]
	v_mfma_f32_16x16x32_bf16 v[104:107], v[140:143], v[172:175], v[104:107]
	v_mfma_f32_16x16x32_bf16 v[92:95], v[132:135], v[180:183], v[92:95]
	v_mfma_f32_16x16x32_bf16 v[88:91], v[140:143], v[180:183], v[88:91]
	v_mfma_f32_16x16x32_bf16 v[76:79], v[132:135], v[204:207], v[76:79]
	v_mfma_f32_16x16x32_bf16 v[72:75], v[140:143], v[204:207], v[72:75]
	s_setprio 0
	s_setprio 1
	v_mfma_f32_16x16x32_bf16 v[116:119], v[144:147], v[160:163], v[116:119]
	v_mfma_f32_16x16x32_bf16 v[112:115], v[152:155], v[160:163], v[112:115]
	v_mfma_f32_16x16x32_bf16 v[100:103], v[144:147], v[168:171], v[100:103]
	v_mfma_f32_16x16x32_bf16 v[96:99], v[152:155], v[168:171], v[96:99]
	v_mfma_f32_16x16x32_bf16 v[84:87], v[144:147], v[176:179], v[84:87]
	v_mfma_f32_16x16x32_bf16 v[80:83], v[152:155], v[176:179], v[80:83]
	v_mfma_f32_16x16x32_bf16 v[68:71], v[144:147], v[200:203], v[68:71]
	v_mfma_f32_16x16x32_bf16 v[64:67], v[152:155], v[200:203], v[64:67]
	s_setprio 2
	s_barrier
	v_mfma_f32_16x16x32_bf16 v[116:119], v[148:151], v[164:167], v[116:119]
	v_mfma_f32_16x16x32_bf16 v[112:115], v[156:159], v[164:167], v[112:115]
	v_mfma_f32_16x16x32_bf16 v[100:103], v[148:151], v[172:175], v[100:103]
	v_mfma_f32_16x16x32_bf16 v[96:99], v[156:159], v[172:175], v[96:99]
	v_mfma_f32_16x16x32_bf16 v[84:87], v[148:151], v[180:183], v[84:87]
	v_mfma_f32_16x16x32_bf16 v[80:83], v[156:159], v[180:183], v[80:83]
	v_mfma_f32_16x16x32_bf16 v[68:71], v[148:151], v[204:207], v[68:71]
	v_mfma_f32_16x16x32_bf16 v[64:67], v[156:159], v[204:207], v[64:67]
	s_setprio 0
	s_add_i32 s67, s62, s49
	v_lshl_add_u64 v[208:209], s[40:41], 0, v[186:187]
	s_mov_b32 m0, s67
	ds_read_b128 v[160:163], v235 offset:16384
	ds_read_b128 v[164:167], v235 offset:17408
	ds_read_b128 v[168:171], v235 offset:18432
	ds_read_b128 v[172:175], v235 offset:19456
	ds_read_b128 v[176:179], v235 offset:20480
	ds_read_b128 v[180:183], v235 offset:21504
	ds_read_b128 v[200:203], v235 offset:22528
	ds_read_b128 v[204:207], v235 offset:23552
	global_load_lds_dwordx4 v[208:209], off
	s_add_i32 m0, s67, 0x2000
	s_add_u32 s68, s40, 0x40000
	v_lshl_add_u64 v[210:211], s[40:41], 0, v[190:191]
	s_addc_u32 s69, s41, 0
	s_add_i32 s67, s63, s49
	global_load_lds_dwordx4 v[210:211], off
	v_lshl_add_u64 v[212:213], s[68:69], 0, v[186:187]
	s_mov_b32 m0, s67
	v_lshl_add_u64 v[214:215], s[42:43], 0, v[188:189]
	global_load_lds_dwordx4 v[212:213], off
	v_lshl_add_u64 v[212:213], s[68:69], 0, v[190:191]
	s_add_i32 m0, s67, 0x2000
	s_nop 0
	global_load_lds_dwordx4 v[212:213], off
	v_lshl_add_u64 v[212:213], s[42:43], 0, v[184:185]
	s_mov_b32 m0, s50
	s_nop 0
	global_load_lds_dwordx4 v[212:213], off
	s_mov_b32 m0, s51
	s_nop 0
	global_load_lds_dwordx4 v[214:215], off
	s_waitcnt vmcnt(8)
	s_waitcnt lgkmcnt(0)
	s_barrier
	s_setprio 1
	s_waitcnt lgkmcnt(0)
	v_mfma_f32_16x16x32_bf16 v[60:63], v[120:123], v[160:163], v[60:63]
	v_mfma_f32_16x16x32_bf16 v[56:59], v[136:139], v[160:163], v[56:59]
	v_mfma_f32_16x16x32_bf16 v[44:47], v[120:123], v[168:171], v[44:47]
	v_mfma_f32_16x16x32_bf16 v[40:43], v[136:139], v[168:171], v[40:43]
	v_mfma_f32_16x16x32_bf16 v[28:31], v[120:123], v[176:179], v[28:31]
	v_mfma_f32_16x16x32_bf16 v[24:27], v[136:139], v[176:179], v[24:27]
	v_mfma_f32_16x16x32_bf16 v[12:15], v[120:123], v[200:203], v[12:15]
	v_mfma_f32_16x16x32_bf16 v[8:11], v[136:139], v[200:203], v[8:11]
	v_mfma_f32_16x16x32_bf16 v[60:63], v[132:135], v[164:167], v[60:63]
	v_mfma_f32_16x16x32_bf16 v[56:59], v[140:143], v[164:167], v[56:59]
	v_mfma_f32_16x16x32_bf16 v[44:47], v[132:135], v[172:175], v[44:47]
	v_mfma_f32_16x16x32_bf16 v[40:43], v[140:143], v[172:175], v[40:43]
	v_mfma_f32_16x16x32_bf16 v[28:31], v[132:135], v[180:183], v[28:31]
	v_mfma_f32_16x16x32_bf16 v[24:27], v[140:143], v[180:183], v[24:27]
	v_mfma_f32_16x16x32_bf16 v[12:15], v[132:135], v[204:207], v[12:15]
	v_mfma_f32_16x16x32_bf16 v[8:11], v[140:143], v[204:207], v[8:11]
	s_setprio 0
	s_setprio 1
	v_mfma_f32_16x16x32_bf16 v[52:55], v[144:147], v[160:163], v[52:55]
	v_mfma_f32_16x16x32_bf16 v[48:51], v[152:155], v[160:163], v[48:51]
	v_mfma_f32_16x16x32_bf16 v[36:39], v[144:147], v[168:171], v[36:39]
	v_mfma_f32_16x16x32_bf16 v[32:35], v[152:155], v[168:171], v[32:35]
	v_mfma_f32_16x16x32_bf16 v[20:23], v[144:147], v[176:179], v[20:23]
	v_mfma_f32_16x16x32_bf16 v[16:19], v[152:155], v[176:179], v[16:19]
	v_mfma_f32_16x16x32_bf16 v[4:7], v[144:147], v[200:203], v[4:7]
	v_mfma_f32_16x16x32_bf16 v[0:3], v[152:155], v[200:203], v[0:3]
	s_setprio 2
	s_barrier
	v_mfma_f32_16x16x32_bf16 v[52:55], v[148:151], v[164:167], v[52:55]
	v_mfma_f32_16x16x32_bf16 v[48:51], v[156:159], v[164:167], v[48:51]
	v_mfma_f32_16x16x32_bf16 v[36:39], v[148:151], v[172:175], v[36:39]
	v_mfma_f32_16x16x32_bf16 v[32:35], v[156:159], v[172:175], v[32:35]
	v_mfma_f32_16x16x32_bf16 v[20:23], v[148:151], v[180:183], v[20:23]
	v_mfma_f32_16x16x32_bf16 v[16:19], v[156:159], v[180:183], v[16:19]
	v_mfma_f32_16x16x32_bf16 v[4:7], v[148:151], v[204:207], v[4:7]
	v_mfma_f32_16x16x32_bf16 v[0:3], v[156:159], v[204:207], v[0:3]
	s_setprio 0
	s_add_i32 s67, 0, 0x18000
	s_add_i32 s68, 0, 0x1c000
	v_add_u32_e32 v140, s67, v232
	v_add_u32_e32 v156, s68, v232
	ds_read_b128 v[120:123], v140
	ds_read_b128 v[132:135], v140 offset:1024
	ds_read_b128 v[136:139], v140 offset:2048
	ds_read_b128 v[140:143], v140 offset:3072
	ds_read_b128 v[144:147], v156
	ds_read_b128 v[148:151], v156 offset:1024
	ds_read_b128 v[152:155], v156 offset:2048
	ds_read_b128 v[156:159], v156 offset:3072
	s_add_u32 s42, s42, 0x40000
	s_addc_u32 s43, s43, 0
	s_mov_b32 m0, s54
	v_lshl_add_u64 v[216:217], s[42:43], 0, v[184:185]
	ds_read_b128 v[160:163], v235 offset:32768
	ds_read_b128 v[164:167], v235 offset:33792
	ds_read_b128 v[168:171], v235 offset:34816
	ds_read_b128 v[172:175], v235 offset:35840
	ds_read_b128 v[176:179], v235 offset:36864
	ds_read_b128 v[180:183], v235 offset:37888
	ds_read_b128 v[200:203], v235 offset:38912
	ds_read_b128 v[204:207], v235 offset:39936
	global_load_lds_dwordx4 v[216:217], off
	v_lshl_add_u64 v[216:217], s[42:43], 0, v[188:189]
	s_mov_b32 m0, s55
	s_nop 0
	global_load_lds_dwordx4 v[216:217], off
	s_waitcnt vmcnt(8)
	s_waitcnt lgkmcnt(0)
	s_barrier
	s_setprio 1
	s_waitcnt lgkmcnt(0)
	v_mfma_f32_16x16x32_bf16 v[128:131], v[120:123], v[160:163], v[128:131]
	v_mfma_f32_16x16x32_bf16 v[124:127], v[136:139], v[160:163], v[124:127]
	v_mfma_f32_16x16x32_bf16 v[108:111], v[120:123], v[168:171], v[108:111]
	v_mfma_f32_16x16x32_bf16 v[104:107], v[136:139], v[168:171], v[104:107]
	v_mfma_f32_16x16x32_bf16 v[92:95], v[120:123], v[176:179], v[92:95]
	v_mfma_f32_16x16x32_bf16 v[88:91], v[136:139], v[176:179], v[88:91]
	v_mfma_f32_16x16x32_bf16 v[76:79], v[120:123], v[200:203], v[76:79]
	v_mfma_f32_16x16x32_bf16 v[72:75], v[136:139], v[200:203], v[72:75]
	v_mfma_f32_16x16x32_bf16 v[128:131], v[132:135], v[164:167], v[128:131]
	v_mfma_f32_16x16x32_bf16 v[124:127], v[140:143], v[164:167], v[124:127]
	v_mfma_f32_16x16x32_bf16 v[108:111], v[132:135], v[172:175], v[108:111]
	v_mfma_f32_16x16x32_bf16 v[104:107], v[140:143], v[172:175], v[104:107]
	v_mfma_f32_16x16x32_bf16 v[92:95], v[132:135], v[180:183], v[92:95]
	v_mfma_f32_16x16x32_bf16 v[88:91], v[140:143], v[180:183], v[88:91]
	v_mfma_f32_16x16x32_bf16 v[76:79], v[132:135], v[204:207], v[76:79]
	v_mfma_f32_16x16x32_bf16 v[72:75], v[140:143], v[204:207], v[72:75]
	s_setprio 0
	s_setprio 1
	v_mfma_f32_16x16x32_bf16 v[116:119], v[144:147], v[160:163], v[116:119]
	v_mfma_f32_16x16x32_bf16 v[112:115], v[152:155], v[160:163], v[112:115]
	v_mfma_f32_16x16x32_bf16 v[100:103], v[144:147], v[168:171], v[100:103]
	v_mfma_f32_16x16x32_bf16 v[96:99], v[152:155], v[168:171], v[96:99]
	v_mfma_f32_16x16x32_bf16 v[84:87], v[144:147], v[176:179], v[84:87]
	v_mfma_f32_16x16x32_bf16 v[80:83], v[152:155], v[176:179], v[80:83]
	v_mfma_f32_16x16x32_bf16 v[68:71], v[144:147], v[200:203], v[68:71]
	v_mfma_f32_16x16x32_bf16 v[64:67], v[152:155], v[200:203], v[64:67]
	s_setprio 2
	s_barrier
	v_mfma_f32_16x16x32_bf16 v[116:119], v[148:151], v[164:167], v[116:119]
	v_mfma_f32_16x16x32_bf16 v[112:115], v[156:159], v[164:167], v[112:115]
	v_mfma_f32_16x16x32_bf16 v[100:103], v[148:151], v[172:175], v[100:103]
	v_mfma_f32_16x16x32_bf16 v[96:99], v[156:159], v[172:175], v[96:99]
	v_mfma_f32_16x16x32_bf16 v[84:87], v[148:151], v[180:183], v[84:87]
	v_mfma_f32_16x16x32_bf16 v[80:83], v[156:159], v[180:183], v[80:83]
	v_mfma_f32_16x16x32_bf16 v[68:71], v[148:151], v[204:207], v[68:71]
	v_mfma_f32_16x16x32_bf16 v[64:67], v[156:159], v[204:207], v[64:67]
	s_setprio 0
	s_add_i32 s42, s67, s49
	v_lshl_add_u64 v[208:209], v[208:209], 0, s[18:19]
	s_mov_b32 m0, s42
	ds_read_b128 v[160:163], v235 offset:49152
	ds_read_b128 v[164:167], v235 offset:50176
	ds_read_b128 v[168:171], v235 offset:51200
	ds_read_b128 v[172:175], v235 offset:52224
	ds_read_b128 v[176:179], v235 offset:53248
	ds_read_b128 v[180:183], v235 offset:54272
	ds_read_b128 v[200:203], v235 offset:55296
	ds_read_b128 v[204:207], v235 offset:56320
	global_load_lds_dwordx4 v[208:209], off
	s_add_i32 m0, s42, 0x2000
	s_add_u32 s40, s40, 0x40080
	v_lshl_add_u64 v[208:209], v[210:211], 0, s[18:19]
	s_addc_u32 s41, s41, 0
	s_add_i32 s42, s68, s49
	global_load_lds_dwordx4 v[208:209], off
	v_lshl_add_u64 v[208:209], s[40:41], 0, v[186:187]
	s_mov_b32 m0, s42
	s_nop 0
	global_load_lds_dwordx4 v[208:209], off
	v_lshl_add_u64 v[208:209], s[40:41], 0, v[190:191]
	s_add_i32 m0, s42, 0x2000
	s_nop 0
	global_load_lds_dwordx4 v[208:209], off
	v_lshl_add_u64 v[208:209], v[212:213], 0, s[18:19]
	s_mov_b32 m0, s57
	s_nop 0
	global_load_lds_dwordx4 v[208:209], off
	v_lshl_add_u64 v[208:209], v[214:215], 0, s[18:19]
	s_mov_b32 m0, s58
	s_nop 0
	global_load_lds_dwordx4 v[208:209], off
	s_waitcnt vmcnt(8)
	s_waitcnt lgkmcnt(0)
	s_barrier
	s_setprio 1
	s_waitcnt lgkmcnt(0)
	v_mfma_f32_16x16x32_bf16 v[60:63], v[120:123], v[160:163], v[60:63]
	v_mfma_f32_16x16x32_bf16 v[56:59], v[136:139], v[160:163], v[56:59]
	v_mfma_f32_16x16x32_bf16 v[44:47], v[120:123], v[168:171], v[44:47]
	v_mfma_f32_16x16x32_bf16 v[40:43], v[136:139], v[168:171], v[40:43]
	v_mfma_f32_16x16x32_bf16 v[28:31], v[120:123], v[176:179], v[28:31]
	v_mfma_f32_16x16x32_bf16 v[24:27], v[136:139], v[176:179], v[24:27]
	v_mfma_f32_16x16x32_bf16 v[12:15], v[120:123], v[200:203], v[12:15]
	v_mfma_f32_16x16x32_bf16 v[8:11], v[136:139], v[200:203], v[8:11]
	v_mfma_f32_16x16x32_bf16 v[60:63], v[132:135], v[164:167], v[60:63]
	v_mfma_f32_16x16x32_bf16 v[56:59], v[140:143], v[164:167], v[56:59]
	v_mfma_f32_16x16x32_bf16 v[44:47], v[132:135], v[172:175], v[44:47]
	v_mfma_f32_16x16x32_bf16 v[40:43], v[140:143], v[172:175], v[40:43]
	v_mfma_f32_16x16x32_bf16 v[28:31], v[132:135], v[180:183], v[28:31]
	v_mfma_f32_16x16x32_bf16 v[24:27], v[140:143], v[180:183], v[24:27]
	v_mfma_f32_16x16x32_bf16 v[12:15], v[132:135], v[204:207], v[12:15]
	v_mfma_f32_16x16x32_bf16 v[8:11], v[140:143], v[204:207], v[8:11]
	s_setprio 0
	s_setprio 1
	v_mfma_f32_16x16x32_bf16 v[52:55], v[144:147], v[160:163], v[52:55]
	v_mfma_f32_16x16x32_bf16 v[48:51], v[152:155], v[160:163], v[48:51]
	v_mfma_f32_16x16x32_bf16 v[36:39], v[144:147], v[168:171], v[36:39]
	v_mfma_f32_16x16x32_bf16 v[32:35], v[152:155], v[168:171], v[32:35]
	v_mfma_f32_16x16x32_bf16 v[20:23], v[144:147], v[176:179], v[20:23]
	v_mfma_f32_16x16x32_bf16 v[16:19], v[152:155], v[176:179], v[16:19]
	v_mfma_f32_16x16x32_bf16 v[4:7], v[144:147], v[200:203], v[4:7]
	v_mfma_f32_16x16x32_bf16 v[0:3], v[152:155], v[200:203], v[0:3]
	s_setprio 2
	s_barrier
	v_mfma_f32_16x16x32_bf16 v[52:55], v[148:151], v[164:167], v[52:55]
	v_mfma_f32_16x16x32_bf16 v[48:51], v[156:159], v[164:167], v[48:51]
	v_mfma_f32_16x16x32_bf16 v[36:39], v[148:151], v[172:175], v[36:39]
	v_mfma_f32_16x16x32_bf16 v[32:35], v[156:159], v[172:175], v[32:35]
	v_mfma_f32_16x16x32_bf16 v[20:23], v[148:151], v[180:183], v[20:23]
	v_mfma_f32_16x16x32_bf16 v[16:19], v[156:159], v[180:183], v[16:19]
	v_mfma_f32_16x16x32_bf16 v[4:7], v[148:151], v[204:207], v[4:7]
	v_mfma_f32_16x16x32_bf16 v[0:3], v[156:159], v[204:207], v[0:3]
	s_setprio 0
	s_add_i32 s66, s66, 2
	s_add_u32 s38, s38, 0x100
	s_addc_u32 s39, s39, 0
	s_add_u32 s64, s64, 0x100
	s_addc_u32 s65, s65, 0
	s_cmp_gt_u32 s66, 13
	s_cbranch_scc0 .LBB0_1146

.LBB0_1310:
	ds_read_b128 v[128:131], v197
	ds_read_b128 v[132:135], v197 offset:1024
	ds_read_b128 v[136:139], v197 offset:2048
	ds_read_b128 v[140:143], v197 offset:3072
	ds_read_b128 v[144:147], v198
	ds_read_b128 v[148:151], v198 offset:1024
	ds_read_b128 v[152:155], v198 offset:2048
	ds_read_b128 v[156:159], v198 offset:3072
	s_add_u32 s4, s24, 0x100
	s_addc_u32 s5, s25, 0
	s_cmp_eq_u32 s53, 40
	s_cselect_b32 s29, s21, s5
	s_cselect_b32 s28, s20, s4
	s_cselect_b32 s27, s23, s52
	s_cselect_b32 s26, s22, s51
	v_lshl_add_u64 v[212:213], s[24:25], 0, v[172:173]
	s_add_i32 m0, s36, 0xc000
	ds_read_b128 v[160:163], v199
	ds_read_b128 v[180:183], v199 offset:1024
	ds_read_b128 v[184:187], v199 offset:2048
	ds_read_b128 v[188:191], v199 offset:3072
	ds_read_b128 v[192:195], v199 offset:4096
	ds_read_b128 v[200:203], v199 offset:5120
	ds_read_b128 v[204:207], v199 offset:6144
	ds_read_b128 v[208:211], v199 offset:7168
	global_load_lds_dwordx4 v[212:213], off
	v_lshl_add_u64 v[212:213], s[24:25], 0, v[174:175]
	s_add_i32 m0, s36, 0xe000
	s_nop 0
	global_load_lds_dwordx4 v[212:213], off
	s_waitcnt vmcnt(8)
	s_waitcnt lgkmcnt(0)
	s_barrier
	s_setprio 1
	s_waitcnt lgkmcnt(0)
	v_mfma_f32_16x16x32_bf16 v[124:127], v[128:131], v[160:163], v[124:127]
	v_mfma_f32_16x16x32_bf16 v[120:123], v[136:139], v[160:163], v[120:123]
	v_mfma_f32_16x16x32_bf16 v[116:119], v[128:131], v[184:187], v[116:119]
	v_mfma_f32_16x16x32_bf16 v[108:111], v[136:139], v[184:187], v[108:111]
	v_mfma_f32_16x16x32_bf16 v[88:91], v[128:131], v[192:195], v[88:91]
	v_mfma_f32_16x16x32_bf16 v[100:103], v[136:139], v[192:195], v[100:103]
	v_mfma_f32_16x16x32_bf16 v[72:75], v[128:131], v[204:207], v[72:75]
	v_mfma_f32_16x16x32_bf16 v[76:79], v[136:139], v[204:207], v[76:79]
	v_mfma_f32_16x16x32_bf16 v[124:127], v[132:135], v[180:183], v[124:127]
	v_mfma_f32_16x16x32_bf16 v[120:123], v[140:143], v[180:183], v[120:123]
	v_mfma_f32_16x16x32_bf16 v[116:119], v[132:135], v[188:191], v[116:119]
	v_mfma_f32_16x16x32_bf16 v[108:111], v[140:143], v[188:191], v[108:111]
	v_mfma_f32_16x16x32_bf16 v[88:91], v[132:135], v[200:203], v[88:91]
	v_mfma_f32_16x16x32_bf16 v[100:103], v[140:143], v[200:203], v[100:103]
	v_mfma_f32_16x16x32_bf16 v[72:75], v[132:135], v[208:211], v[72:75]
	v_mfma_f32_16x16x32_bf16 v[76:79], v[140:143], v[208:211], v[76:79]
	s_setprio 0
	s_setprio 1
	v_mfma_f32_16x16x32_bf16 v[112:115], v[144:147], v[160:163], v[112:115]
	v_mfma_f32_16x16x32_bf16 v[104:107], v[152:155], v[160:163], v[104:107]
	v_mfma_f32_16x16x32_bf16 v[96:99], v[144:147], v[184:187], v[96:99]
	v_mfma_f32_16x16x32_bf16 v[92:95], v[152:155], v[184:187], v[92:95]
	v_mfma_f32_16x16x32_bf16 v[80:83], v[144:147], v[192:195], v[80:83]
	v_mfma_f32_16x16x32_bf16 v[84:87], v[152:155], v[192:195], v[84:87]
	v_mfma_f32_16x16x32_bf16 v[64:67], v[144:147], v[204:207], v[64:67]
	v_mfma_f32_16x16x32_bf16 v[68:71], v[152:155], v[204:207], v[68:71]
	s_setprio 2
	s_barrier
	v_mfma_f32_16x16x32_bf16 v[112:115], v[148:151], v[180:183], v[112:115]
	v_mfma_f32_16x16x32_bf16 v[104:107], v[156:159], v[180:183], v[104:107]
	v_mfma_f32_16x16x32_bf16 v[96:99], v[148:151], v[188:191], v[96:99]
	v_mfma_f32_16x16x32_bf16 v[92:95], v[156:159], v[188:191], v[92:95]
	v_mfma_f32_16x16x32_bf16 v[80:83], v[148:151], v[200:203], v[80:83]
	v_mfma_f32_16x16x32_bf16 v[84:87], v[156:159], v[200:203], v[84:87]
	v_mfma_f32_16x16x32_bf16 v[64:67], v[148:151], v[208:211], v[64:67]
	v_mfma_f32_16x16x32_bf16 v[68:71], v[156:159], v[208:211], v[68:71]
	s_setprio 0
	s_add_i32 s24, s45, s35
	v_lshl_add_u64 v[212:213], s[26:27], 0, v[166:167]
	s_mov_b32 m0, s24
	ds_read_b128 v[160:163], v199 offset:16384
	ds_read_b128 v[180:183], v199 offset:17408
	ds_read_b128 v[184:187], v199 offset:18432
	ds_read_b128 v[188:191], v199 offset:19456
	ds_read_b128 v[192:195], v199 offset:20480
	ds_read_b128 v[200:203], v199 offset:21504
	ds_read_b128 v[204:207], v199 offset:22528
	ds_read_b128 v[208:211], v199 offset:23552
	global_load_lds_dwordx4 v[212:213], off
	s_add_i32 m0, s24, 0x2000
	s_add_u32 s24, s26, 0xb0000
	v_lshl_add_u64 v[214:215], s[26:27], 0, v[170:171]
	s_addc_u32 s25, s27, 0
	s_add_i32 s54, s46, s35
	global_load_lds_dwordx4 v[214:215], off
	v_lshl_add_u64 v[216:217], s[24:25], 0, v[166:167]
	s_mov_b32 m0, s54
	v_lshl_add_u64 v[218:219], s[28:29], 0, v[168:169]
	global_load_lds_dwordx4 v[216:217], off
	v_lshl_add_u64 v[216:217], s[24:25], 0, v[170:171]
	s_add_i32 m0, s54, 0x2000
	s_nop 0
	global_load_lds_dwordx4 v[216:217], off
	v_lshl_add_u64 v[216:217], s[28:29], 0, v[164:165]
	s_mov_b32 m0, s36
	s_nop 0
	global_load_lds_dwordx4 v[216:217], off
	s_mov_b32 m0, s37
	s_nop 0
	global_load_lds_dwordx4 v[218:219], off
	s_waitcnt vmcnt(8)
	s_waitcnt lgkmcnt(0)
	s_barrier
	s_setprio 1
	s_waitcnt lgkmcnt(0)
	v_mfma_f32_16x16x32_bf16 v[56:59], v[128:131], v[160:163], v[56:59]
	v_mfma_f32_16x16x32_bf16 v[60:63], v[136:139], v[160:163], v[60:63]
	v_mfma_f32_16x16x32_bf16 v[40:43], v[128:131], v[184:187], v[40:43]
	v_mfma_f32_16x16x32_bf16 v[44:47], v[136:139], v[184:187], v[44:47]
	v_mfma_f32_16x16x32_bf16 v[24:27], v[128:131], v[192:195], v[24:27]
	v_mfma_f32_16x16x32_bf16 v[28:31], v[136:139], v[192:195], v[28:31]
	v_mfma_f32_16x16x32_bf16 v[8:11], v[128:131], v[204:207], v[8:11]
	v_mfma_f32_16x16x32_bf16 v[12:15], v[136:139], v[204:207], v[12:15]
	v_mfma_f32_16x16x32_bf16 v[56:59], v[132:135], v[180:183], v[56:59]
	v_mfma_f32_16x16x32_bf16 v[60:63], v[140:143], v[180:183], v[60:63]
	v_mfma_f32_16x16x32_bf16 v[40:43], v[132:135], v[188:191], v[40:43]
	v_mfma_f32_16x16x32_bf16 v[44:47], v[140:143], v[188:191], v[44:47]
	v_mfma_f32_16x16x32_bf16 v[24:27], v[132:135], v[200:203], v[24:27]
	v_mfma_f32_16x16x32_bf16 v[28:31], v[140:143], v[200:203], v[28:31]
	v_mfma_f32_16x16x32_bf16 v[8:11], v[132:135], v[208:211], v[8:11]
	v_mfma_f32_16x16x32_bf16 v[12:15], v[140:143], v[208:211], v[12:15]
	s_setprio 0
	s_setprio 1
	v_mfma_f32_16x16x32_bf16 v[48:51], v[144:147], v[160:163], v[48:51]
	v_mfma_f32_16x16x32_bf16 v[52:55], v[152:155], v[160:163], v[52:55]
	v_mfma_f32_16x16x32_bf16 v[32:35], v[144:147], v[184:187], v[32:35]
	v_mfma_f32_16x16x32_bf16 v[36:39], v[152:155], v[184:187], v[36:39]
	v_mfma_f32_16x16x32_bf16 v[16:19], v[144:147], v[192:195], v[16:19]
	v_mfma_f32_16x16x32_bf16 v[20:23], v[152:155], v[192:195], v[20:23]
	v_mfma_f32_16x16x32_bf16 v[0:3], v[144:147], v[204:207], v[0:3]
	v_mfma_f32_16x16x32_bf16 v[4:7], v[152:155], v[204:207], v[4:7]
	s_setprio 2
	s_barrier
	v_mfma_f32_16x16x32_bf16 v[48:51], v[148:151], v[180:183], v[48:51]
	v_mfma_f32_16x16x32_bf16 v[52:55], v[156:159], v[180:183], v[52:55]
	v_mfma_f32_16x16x32_bf16 v[32:35], v[148:151], v[188:191], v[32:35]
	v_mfma_f32_16x16x32_bf16 v[36:39], v[156:159], v[188:191], v[36:39]
	v_mfma_f32_16x16x32_bf16 v[16:19], v[148:151], v[200:203], v[16:19]
	v_mfma_f32_16x16x32_bf16 v[20:23], v[156:159], v[200:203], v[20:23]
	v_mfma_f32_16x16x32_bf16 v[0:3], v[148:151], v[208:211], v[0:3]
	v_mfma_f32_16x16x32_bf16 v[4:7], v[156:159], v[208:211], v[4:7]
	s_setprio 0
	s_add_i32 s54, 0, 0x18000
	s_add_i32 s55, 0, 0x1c000
	v_add_u32_e32 v140, s54, v196
	v_add_u32_e32 v156, s55, v196
	ds_read_b128 v[128:131], v140
	ds_read_b128 v[132:135], v140 offset:1024
	ds_read_b128 v[136:139], v140 offset:2048
	ds_read_b128 v[140:143], v140 offset:3072
	ds_read_b128 v[144:147], v156
	ds_read_b128 v[148:151], v156 offset:1024
	ds_read_b128 v[152:155], v156 offset:2048
	ds_read_b128 v[156:159], v156 offset:3072
	s_add_u32 s24, s28, 0xb0000
	s_addc_u32 s25, s29, 0
	s_mov_b32 m0, s38
	v_lshl_add_u64 v[220:221], s[24:25], 0, v[164:165]
	ds_read_b128 v[160:163], v199 offset:32768
	ds_read_b128 v[180:183], v199 offset:33792
	ds_read_b128 v[184:187], v199 offset:34816
	ds_read_b128 v[188:191], v199 offset:35840
	ds_read_b128 v[192:195], v199 offset:36864
	ds_read_b128 v[200:203], v199 offset:37888
	ds_read_b128 v[204:207], v199 offset:38912
	ds_read_b128 v[208:211], v199 offset:39936
	global_load_lds_dwordx4 v[220:221], off
	v_lshl_add_u64 v[220:221], s[24:25], 0, v[168:169]
	s_mov_b32 m0, s39
	s_nop 0
	global_load_lds_dwordx4 v[220:221], off
	s_waitcnt vmcnt(8)
	s_waitcnt lgkmcnt(0)
	s_barrier
	s_setprio 1
	s_waitcnt lgkmcnt(0)
	v_mfma_f32_16x16x32_bf16 v[124:127], v[128:131], v[160:163], v[124:127]
	v_mfma_f32_16x16x32_bf16 v[120:123], v[136:139], v[160:163], v[120:123]
	v_mfma_f32_16x16x32_bf16 v[116:119], v[128:131], v[184:187], v[116:119]
	v_mfma_f32_16x16x32_bf16 v[108:111], v[136:139], v[184:187], v[108:111]
	v_mfma_f32_16x16x32_bf16 v[88:91], v[128:131], v[192:195], v[88:91]
	v_mfma_f32_16x16x32_bf16 v[100:103], v[136:139], v[192:195], v[100:103]
	v_mfma_f32_16x16x32_bf16 v[72:75], v[128:131], v[204:207], v[72:75]
	v_mfma_f32_16x16x32_bf16 v[76:79], v[136:139], v[204:207], v[76:79]
	v_mfma_f32_16x16x32_bf16 v[124:127], v[132:135], v[180:183], v[124:127]
	v_mfma_f32_16x16x32_bf16 v[120:123], v[140:143], v[180:183], v[120:123]
	v_mfma_f32_16x16x32_bf16 v[116:119], v[132:135], v[188:191], v[116:119]
	v_mfma_f32_16x16x32_bf16 v[108:111], v[140:143], v[188:191], v[108:111]
	v_mfma_f32_16x16x32_bf16 v[88:91], v[132:135], v[200:203], v[88:91]
	v_mfma_f32_16x16x32_bf16 v[100:103], v[140:143], v[200:203], v[100:103]
	v_mfma_f32_16x16x32_bf16 v[72:75], v[132:135], v[208:211], v[72:75]
	v_mfma_f32_16x16x32_bf16 v[76:79], v[140:143], v[208:211], v[76:79]
	s_setprio 0
	s_setprio 1
	v_mfma_f32_16x16x32_bf16 v[112:115], v[144:147], v[160:163], v[112:115]
	v_mfma_f32_16x16x32_bf16 v[104:107], v[152:155], v[160:163], v[104:107]
	v_mfma_f32_16x16x32_bf16 v[96:99], v[144:147], v[184:187], v[96:99]
	v_mfma_f32_16x16x32_bf16 v[92:95], v[152:155], v[184:187], v[92:95]
	v_mfma_f32_16x16x32_bf16 v[80:83], v[144:147], v[192:195], v[80:83]
	v_mfma_f32_16x16x32_bf16 v[84:87], v[152:155], v[192:195], v[84:87]
	v_mfma_f32_16x16x32_bf16 v[64:67], v[144:147], v[204:207], v[64:67]
	v_mfma_f32_16x16x32_bf16 v[68:71], v[152:155], v[204:207], v[68:71]
	s_setprio 2
	s_barrier
	v_mfma_f32_16x16x32_bf16 v[112:115], v[148:151], v[180:183], v[112:115]
	v_mfma_f32_16x16x32_bf16 v[104:107], v[156:159], v[180:183], v[104:107]
	v_mfma_f32_16x16x32_bf16 v[96:99], v[148:151], v[188:191], v[96:99]
	v_mfma_f32_16x16x32_bf16 v[92:95], v[156:159], v[188:191], v[92:95]
	v_mfma_f32_16x16x32_bf16 v[80:83], v[148:151], v[200:203], v[80:83]
	v_mfma_f32_16x16x32_bf16 v[84:87], v[156:159], v[200:203], v[84:87]
	v_mfma_f32_16x16x32_bf16 v[64:67], v[148:151], v[208:211], v[64:67]
	v_mfma_f32_16x16x32_bf16 v[68:71], v[156:159], v[208:211], v[68:71]
	s_setprio 0
	s_add_i32 s24, s54, s35
	v_lshl_add_u64 v[212:213], v[212:213], 0, s[16:17]
	s_mov_b32 m0, s24
	ds_read_b128 v[160:163], v199 offset:49152
	ds_read_b128 v[180:183], v199 offset:50176
	ds_read_b128 v[184:187], v199 offset:51200
	ds_read_b128 v[188:191], v199 offset:52224
	ds_read_b128 v[192:195], v199 offset:53248
	ds_read_b128 v[200:203], v199 offset:54272
	ds_read_b128 v[204:207], v199 offset:55296
	ds_read_b128 v[208:211], v199 offset:56320
	global_load_lds_dwordx4 v[212:213], off
	s_add_i32 m0, s24, 0x2000
	s_add_u32 s24, s26, 0xb0080
	v_lshl_add_u64 v[212:213], v[214:215], 0, s[16:17]
	s_addc_u32 s25, s27, 0
	s_add_i32 s26, s55, s35
	global_load_lds_dwordx4 v[212:213], off
	v_lshl_add_u64 v[212:213], s[24:25], 0, v[166:167]
	s_mov_b32 m0, s26
	s_nop 0
	global_load_lds_dwordx4 v[212:213], off
	v_lshl_add_u64 v[212:213], s[24:25], 0, v[170:171]
	s_add_i32 m0, s26, 0x2000
	s_nop 0
	global_load_lds_dwordx4 v[212:213], off
	v_lshl_add_u64 v[212:213], v[216:217], 0, s[16:17]
	s_mov_b32 m0, s41
	s_nop 0
	global_load_lds_dwordx4 v[212:213], off
	v_lshl_add_u64 v[212:213], v[218:219], 0, s[16:17]
	s_mov_b32 m0, s42
	s_nop 0
	global_load_lds_dwordx4 v[212:213], off
	s_waitcnt vmcnt(8)
	s_waitcnt lgkmcnt(0)
	s_barrier
	s_setprio 1
	s_waitcnt lgkmcnt(0)
	v_mfma_f32_16x16x32_bf16 v[56:59], v[128:131], v[160:163], v[56:59]
	v_mfma_f32_16x16x32_bf16 v[60:63], v[136:139], v[160:163], v[60:63]
	v_mfma_f32_16x16x32_bf16 v[40:43], v[128:131], v[184:187], v[40:43]
	v_mfma_f32_16x16x32_bf16 v[44:47], v[136:139], v[184:187], v[44:47]
	v_mfma_f32_16x16x32_bf16 v[24:27], v[128:131], v[192:195], v[24:27]
	v_mfma_f32_16x16x32_bf16 v[28:31], v[136:139], v[192:195], v[28:31]
	v_mfma_f32_16x16x32_bf16 v[8:11], v[128:131], v[204:207], v[8:11]
	v_mfma_f32_16x16x32_bf16 v[12:15], v[136:139], v[204:207], v[12:15]
	v_mfma_f32_16x16x32_bf16 v[56:59], v[132:135], v[180:183], v[56:59]
	v_mfma_f32_16x16x32_bf16 v[60:63], v[140:143], v[180:183], v[60:63]
	v_mfma_f32_16x16x32_bf16 v[40:43], v[132:135], v[188:191], v[40:43]
	v_mfma_f32_16x16x32_bf16 v[44:47], v[140:143], v[188:191], v[44:47]
	v_mfma_f32_16x16x32_bf16 v[24:27], v[132:135], v[200:203], v[24:27]
	v_mfma_f32_16x16x32_bf16 v[28:31], v[140:143], v[200:203], v[28:31]
	v_mfma_f32_16x16x32_bf16 v[8:11], v[132:135], v[208:211], v[8:11]
	v_mfma_f32_16x16x32_bf16 v[12:15], v[140:143], v[208:211], v[12:15]
	s_setprio 0
	s_setprio 1
	v_mfma_f32_16x16x32_bf16 v[48:51], v[144:147], v[160:163], v[48:51]
	v_mfma_f32_16x16x32_bf16 v[52:55], v[152:155], v[160:163], v[52:55]
	v_mfma_f32_16x16x32_bf16 v[32:35], v[144:147], v[184:187], v[32:35]
	v_mfma_f32_16x16x32_bf16 v[36:39], v[152:155], v[184:187], v[36:39]
	v_mfma_f32_16x16x32_bf16 v[16:19], v[144:147], v[192:195], v[16:19]
	v_mfma_f32_16x16x32_bf16 v[20:23], v[152:155], v[192:195], v[20:23]
	v_mfma_f32_16x16x32_bf16 v[0:3], v[144:147], v[204:207], v[0:3]
	v_mfma_f32_16x16x32_bf16 v[4:7], v[152:155], v[204:207], v[4:7]
	s_setprio 2
	s_barrier
	v_mfma_f32_16x16x32_bf16 v[48:51], v[148:151], v[180:183], v[48:51]
	v_mfma_f32_16x16x32_bf16 v[52:55], v[156:159], v[180:183], v[52:55]
	v_mfma_f32_16x16x32_bf16 v[32:35], v[148:151], v[188:191], v[32:35]
	v_mfma_f32_16x16x32_bf16 v[36:39], v[156:159], v[188:191], v[36:39]
	v_mfma_f32_16x16x32_bf16 v[16:19], v[148:151], v[200:203], v[16:19]
	v_mfma_f32_16x16x32_bf16 v[20:23], v[156:159], v[200:203], v[20:23]
	v_mfma_f32_16x16x32_bf16 v[0:3], v[148:151], v[208:211], v[0:3]
	v_mfma_f32_16x16x32_bf16 v[4:7], v[156:159], v[208:211], v[4:7]
	s_setprio 0
	s_add_i32 s53, s53, 2
	s_add_u32 s51, s51, 0x100
	s_addc_u32 s52, s52, 0
	s_cmp_gt_u32 s53, 41
	s_mov_b64 s[24:25], s[4:5]
	s_cbranch_scc0 .LBB0_1310
